# P3: u rows of two experts per global_load_dwordx4 (half-wave per row), dot products on 32 nibbles per lane, unchanged butterfly
# baseline (speedup 1.0000x reference)
; __device__ __forceinline__ float bf_lo(unsigned u) { return __uint_as_float(u << 16); }
; __device__ __forceinline__ float bf_hi(unsigned u) { return __uint_as_float(u & 0xffff0000u); }
; __device__ __forceinline__ int vblk() { return (int)blockIdx.x * 2 + half_id(); }
; __device__ __forceinline__ int vgrid() { return (int)gridDim.x * 2; }
; __device__ __forceinline__ void p3_token(const Params& p, int tok, int lane, unsigned* rec, float& sh, int& hs8) {
;     const bf16_t* H = (const bf16_t*)(p.ws + OFF_H);
;     const int* eidx = (const int*)(p.ws + OFF_EIDX);
;     const float* gwp = (const float*)(p.ws + OFF_GW);
;     {
;         const u32x4 a = *(const u32x4*)(H + (size_t)tok * DM + lane * 16), b = *(const u32x4*)(H + (size_t)tok * DM + lane * 16 + 8);
;         const unsigned hw[8] = {a.x, a.y, a.z, a.w, b.x, b.y, b.z, b.w};
;         float hv[16];
;         float mx = 0.f;
; #pragma unroll
;         for (int i = 0; i < 8; i++) { hv[2 * i] = bf_lo(hw[i]); hv[2 * i + 1] = bf_hi(hw[i]); mx = fmaxf(mx, fmaxf(fabsf(hv[2 * i]), fabsf(hv[2 * i + 1]))); }
;         mx = wave_max(mx);
; __device__ void phaseP3(const Params& p, float* dstp, char* lds) {
;     const int tid_ = TIDX; const int lane = tid_ & 63, wave = tid_ >> 6;
;     const unsigned char* UQ = (const unsigned char*)(p.ws + OFF_UB);
;     const unsigned char* VQ = UQ + 16777216;
;     const float* tsc = (const float*)(p.ws + OFF_UB + 33554432);
;     const int ul = ((lane & 1) << 1) | ((lane >> 1) & 1);
;     constexpr int TPW = 2;
;     unsigned* recs = (unsigned*)(lds + wave * TPW * P3_REC);
;     for (int tb = (vblk() * 4 + wave) * TPW; tb < NTOK; tb += vgrid() * 4 * TPW) {
.LBB0_1040:
	s_or_b64 exec, exec, s[4:5]
	v_readfirstlane_b32 s0, v158
	v_readlane_b32 s1, v222, 0
	s_lshr_b32 s0, s0, 5
	v_mov_b32_e32 v1, v158
	s_lshl_b32 s1, s1, 4
	s_and_b32 s0, s0, 0x7fffff8
	s_waitcnt lgkmcnt(0)
	s_barrier
	s_add_i32 s0, s0, s1
	v_bfe_u32 v0, v1, 6, 2
	v_lshl_or_b32 v8, v0, 1, s0
	s_movk_i32 s0, 0x4000
	v_cmp_gt_i32_e32 vcc, s0, v8
	s_and_saveexec_b64 s[0:1], vcc
	s_cbranch_execz .LBB0_1077
	s_movk_i32 s8, 0x1400
	v_mov_b32_e32 v2, s33
	v_mad_u32_u24 v11, v0, s8, v2
	v_and_b32_e32 v2, 64, v159
	v_add_u32_e32 v2, 64, v2
	v_xor_b32_e32 v3, 32, v159
	v_cmp_lt_i32_e32 vcc, v3, v2
	s_load_dwordx4 s[20:23], s[80:81], 0xd0
	s_load_dwordx2 s[4:5], s[80:81], 0x38
	v_cndmask_b32_e32 v3, v159, v3, vcc
	v_lshlrev_b32_e32 v112, 2, v3
	v_xor_b32_e32 v3, 16, v159
	v_cmp_lt_i32_e32 vcc, v3, v2
	v_and_b32_e32 v10, 63, v1
	v_mov_b32_e32 v13, 0
	v_cndmask_b32_e32 v3, v159, v3, vcc
	v_lshlrev_b32_e32 v113, 2, v3
	v_xor_b32_e32 v3, 8, v159
	v_cmp_lt_i32_e32 vcc, v3, v2
	v_lshlrev_b32_e32 v12, 4, v10
	s_mov_b64 s[0:1], 0x9c00000
	v_cndmask_b32_e32 v3, v159, v3, vcc
	v_lshlrev_b32_e32 v114, 2, v3
	v_xor_b32_e32 v3, 4, v159
	v_cmp_lt_i32_e32 vcc, v3, v2
	s_lshl_b32 s36, s72, 4
	v_bfrev_b32_e32 v4, v1
	v_cndmask_b32_e32 v3, v159, v3, vcc
	v_lshlrev_b32_e32 v115, 2, v3
	v_xor_b32_e32 v3, 2, v159
	v_cmp_lt_i32_e32 vcc, v3, v2
	s_waitcnt vmcnt(3) lgkmcnt(0)
	v_lshl_add_u64 v[18:19], s[20:21], 0, v[12:13]
	s_add_u32 s20, s22, 0xdd00000
	v_cndmask_b32_e32 v3, v159, v3, vcc
	v_lshlrev_b32_e32 v116, 2, v3
	v_xor_b32_e32 v3, 1, v159
	v_cmp_lt_i32_e32 vcc, v3, v2
	s_addc_u32 s21, s23, 0
	v_mov_b32_e32 v5, v13
	v_cndmask_b32_e32 v2, v159, v3, vcc
	v_lshlrev_b32_e32 v117, 2, v2
	v_lshlrev_b32_e32 v2, 3, v10
	v_mov_b32_e32 v3, v13
	v_lshl_add_u64 v[2:3], s[22:23], 0, v[2:3]
	v_lshl_add_u64 v[14:15], v[2:3], 0, s[0:1]
	s_mov_b64 s[0:1], 0xac00000
	v_lshl_add_u64 v[16:17], v[2:3], 0, s[0:1]
	v_and_b32_e32 v2, 1, v1
	v_lshrrev_b32_e32 v3, 28, v4
	v_cmp_eq_u32_e64 s[0:1], 0, v2
	v_lshlrev_b32_e32 v2, 6, v10
	v_and_b32_e32 v6, 12, v3
	v_lshlrev_b32_e32 v4, 5, v10
	s_add_u32 s24, s22, 0xe500000
	v_mov_b32_e32 v3, v13
	v_and_b32_e32 v1, 2, v1
	v_add_u32_e32 v118, v11, v2
	v_lshl_add_u64 v[4:5], s[22:23], 0, v[4:5]
	s_mov_b64 s[6:7], 0x1c00000
	s_addc_u32 s25, s23, 0
	s_waitcnt vmcnt(1)
	v_lshl_add_u64 v[24:25], s[4:5], 0, v[2:3]
	v_mov_b32_e32 v2, s33
	v_cmp_eq_u32_e64 s[2:3], 0, v1
	v_mul_i32_i24_e32 v1, 0xffffffd0, v10
	v_lshl_add_u64 v[20:21], v[4:5], 0, s[6:7]
	s_add_u32 s26, s22, 0xbc00000
	s_mov_b64 s[6:7], 0xbd00000
	v_mad_u32_u24 v0, v0, s8, v2
	s_movk_i32 s4, 0x210
	v_add_u32_e32 v119, v11, v6
	s_addc_u32 s27, s23, 0
	v_lshl_add_u64 v[22:23], v[4:5], 0, s[6:7]
	v_add3_u32 v120, v0, v6, s4
	v_add_u32_e32 v121, 16, v0
	s_mov_b64 s[28:29], 0
	s_mov_b32 s33, 0x42ee0000
	v_mov_b32_e32 v122, 0x80
	s_movk_i32 s37, 0x800
	v_mov_b32_e32 v123, 0x800
	v_mov_b32_e32 v124, 0x8000
	v_mov_b32_e32 v125, 0x80000
	s_mov_b32 s38, 0x800000
	v_mov_b32_e32 v126, 0x800000
	v_bfrev_b32_e32 v127, 16
	v_add_u32_e32 v128, v118, v1
	s_mov_b32 s39, 0x3e6d3388
	v_mov_b32_e32 v129, 0xbf3a00e3
	v_lshlrev_b32_e32 v26, 2, v12
	s_mov_b64 s[30:31], 0x9000
	s_mov_b32 s40, 0x9000
	v_mov_b32_e32 v130, 0x358637bd
	s_movk_i32 s41, 0x3fff
	s_add_u32 s50, s22, 0x9c00000
	s_addc_u32 s51, s23, 0
	s_add_u32 s52, s22, 0xac00000
	s_addc_u32 s53, s23, 0
	v_lshlrev_b32_e32 v136, 3, v159
	v_and_b32_e32 v138, 16, v159
	v_mov_b32_e32 v137, 0xa00
	v_cmp_ne_u32_e64 s[54:55], 0, v138
	s_nop 1
	v_cndmask_b32_e64 v137, 0, v137, s[54:55]
	v_add_u32_e32 v137, v120, v137
	v_readfirstlane_b32 s56, v158
	s_lshr_b32 s57, s56, 8
	s_mul_i32 s57, s57, 0x12000
	s_lshr_b32 s56, s56, 6
	s_and_b32 s56, s56, 3
	s_lshl_b32 s56, s56, 12
	s_add_i32 s56, s56, s57
	s_add_i32 s56, s56, 0x8000
	v_and_b32_e32 v148, 31, v159
	v_lshlrev_b32_e32 v148, 4, v148
	v_lshl_add_u32 v149, v159, 3, s56
	v_lshl_add_u32 v154, v159, 4, s56
	s_mov_b32 s58, -1
	s_mov_b32 s59, 0
.LBB0_1042:
	v_ashrrev_i32_e32 v9, 31, v8
	s_waitcnt vmcnt(0)
	v_lshlrev_b64 v[28:29], 11, v[8:9]
	v_lshl_add_u64 v[30:31], v[20:21], 0, v[28:29]
	global_load_dwordx4 v[0:3], v[30:31], off
	global_load_dwordx4 v[4:7], v[30:31], off offset:16
	s_waitcnt vmcnt(1)
	v_lshlrev_b32_e32 v12, 16, v0
	v_and_b32_e32 v27, 0xffff0000, v0
	v_lshlrev_b32_e32 v36, 16, v1
	v_and_b32_e32 v37, 0xffff0000, v1
	v_lshlrev_b32_e32 v38, 16, v2
	v_and_b32_e32 v39, 0xffff0000, v2
	v_lshlrev_b32_e32 v40, 16, v3
	v_and_b32_e32 v41, 0xffff0000, v3
	v_max_f32_e64 v0, |v27|, |v27|
	v_max_f32_e64 v1, |v12|, |v12|
	v_max_f32_e64 v2, |v37|, |v37|
	v_max_f32_e64 v3, |v36|, |v36|
	s_waitcnt vmcnt(0)
	v_lshlrev_b32_e32 v42, 16, v4
	v_and_b32_e32 v43, 0xffff0000, v4
	v_lshlrev_b32_e32 v44, 16, v5
	v_and_b32_e32 v5, 0xffff0000, v5
	v_lshlrev_b32_e32 v45, 16, v6
	v_and_b32_e32 v46, 0xffff0000, v6
	v_lshlrev_b32_e32 v47, 16, v7
	v_and_b32_e32 v48, 0xffff0000, v7
	v_max_f32_e64 v4, |v39|, |v39|
	v_max_f32_e64 v6, |v38|, |v38|
	v_max_f32_e64 v7, |v41|, |v41|
	v_max_f32_e64 v30, |v40|, |v40|
	v_max_f32_e32 v0, v1, v0
	v_max_f32_e32 v1, v3, v2
	v_max_f32_e64 v31, |v43|, |v43|
	v_max_f32_e64 v32, |v42|, |v42|
	v_max_f32_e64 v33, |v5|, |v5|
	v_max_f32_e64 v34, |v44|, |v44|
	v_max_f32_e32 v2, v6, v4
	v_max_f32_e32 v3, v30, v7
	v_max3_f32 v0, v0, 0, v1
	v_max_f32_e64 v35, |v46|, |v46|
	v_max_f32_e64 v49, |v45|, |v45|
	v_max_f32_e64 v50, |v48|, |v48|
	v_max_f32_e64 v51, |v47|, |v47|
	v_max_f32_e32 v4, v32, v31
	v_max_f32_e32 v6, v34, v33
	v_max3_f32 v0, v0, v2, v3
	v_max_f32_e32 v7, v49, v35
	v_max_f32_e32 v30, v51, v50
	v_max3_f32 v0, v0, v4, v6
	v_max3_f32 v0, v0, v7, v30
	ds_bpermute_b32 v1, v112, v0
	s_waitcnt lgkmcnt(0)
; __device__ __forceinline__ void p3_token(const Params& p, int tok, int lane, unsigned* rec, float& sh, int& hs8) {
;     ...
;         mx = wave_max(mx);
;         const float inv = mx > 0.f ? 119.f / mx : 0.f;
;         sh = mx * (1.f / 119.f);
;         unsigned qh[4] = {0u, 0u, 0u, 0u};
; #pragma unroll
;         for (int e = 0; e < 16; e++) {
;             const int qi = (int)rintf(hv[e] * inv);
;             const int hh = (qi + 8) >> 4, hl = qi - 16 * hh;
;             qh[(e >> 3) * 2] |= (unsigned)(hh & 15) << ((e & 7) * 4);
;             qh[(e >> 3) * 2 + 1] |= (unsigned)(hl & 15) << ((e & 7) * 4);
;         }
;         hs8 = 0;
;         *(u32x4*)(rec + 256 + lane * 4) = (u32x4){qh[0], qh[1], qh[2], qh[3]};
;     }
;     const int e0 = eidx[(size_t)tok * 128 + lane], e1 = eidx[(size_t)tok * 128 + 64 + lane];
;     const float g0 = gwp[(size_t)tok * 128 + lane], g1 = gwp[(size_t)tok * 128 + 64 + lane];
;     const int k0 = e0 >> 11, k1 = e1 >> 11;
;     int pos0 = 0, pos1 = 0, base = 0;
; #pragma unroll
;     for (int v = 0; v < 8; v++) {
;         const unsigned long long m0 = __ballot(k0 == v), m1 = __ballot(k1 == v);
;         const int c0 = __popcll(m0);
;         const int r0 = __builtin_amdgcn_mbcnt_hi((unsigned)(m0 >> 32), __builtin_amdgcn_mbcnt_lo((unsigned)m0, 0u));
;         const int r1 = __builtin_amdgcn_mbcnt_hi((unsigned)(m1 >> 32), __builtin_amdgcn_mbcnt_lo((unsigned)m1, 0u));
;         pos0 = (k0 == v) ? base + r0 : pos0;
;         pos1 = (k1 == v) ? base + c0 + r1 : pos1;
;         base += c0 + __popcll(m1);
	v_max_f32_e32 v1, v1, v1
	v_max_f32_e32 v0, v0, v1
	ds_bpermute_b32 v1, v113, v0
	s_waitcnt lgkmcnt(0)
	v_max_f32_e32 v1, v1, v1
	v_max_f32_e32 v0, v0, v1
	ds_bpermute_b32 v1, v114, v0
	s_waitcnt lgkmcnt(0)
	v_max_f32_e32 v1, v1, v1
	v_max_f32_e32 v0, v0, v1
	ds_bpermute_b32 v1, v115, v0
	s_waitcnt lgkmcnt(0)
	v_max_f32_e32 v1, v1, v1
	v_max_f32_e32 v2, v0, v1
	ds_bpermute_b32 v4, v116, v2
	v_lshlrev_b64 v[0:1], 9, v[8:9]
	v_lshl_or_b32 v0, v10, 2, v0
	v_mov_b32_e32 v3, v1
	v_lshl_add_u64 v[6:7], s[20:21], 0, v[0:1]
	s_waitcnt lgkmcnt(0)
	v_max_f32_e32 v4, v4, v4
	v_max_f32_e32 v4, v2, v4
	ds_bpermute_b32 v49, v117, v4
	v_or_b32_e32 v2, 0x100, v0
	v_lshl_add_u64 v[30:31], s[24:25], 0, v[0:1]
	v_lshl_add_u64 v[32:33], s[20:21], 0, v[2:3]
	v_lshl_add_u64 v[34:35], s[24:25], 0, v[2:3]
	s_waitcnt lgkmcnt(0)
	v_max_f32_e32 v0, v49, v49
	v_max_f32_e32 v0, v4, v0
	global_load_dword v4, v[6:7], off
	global_load_dword v1, v[32:33], off
	global_load_dword v2, v[30:31], off
	global_load_dword v3, v[34:35], off
	v_div_scale_f32 v49, s[4:5], v0, v0, s33
	v_rcp_f32_e32 v50, v49
	v_div_scale_f32 v6, vcc, s33, v0, s33
	v_fma_f32 v7, -v49, v50, 1.0
	v_fmac_f32_e32 v50, v7, v50
	v_mul_f32_e32 v7, v6, v50
	v_fma_f32 v30, -v49, v7, v6
	v_fmac_f32_e32 v7, v30, v50
	v_fma_f32 v6, -v49, v7, v6
	v_div_fmas_f32 v6, v6, v50, v7
	v_div_fixup_f32 v6, v6, v0, s33
	v_cmp_lt_f32_e32 vcc, 0, v0
	s_waitcnt vmcnt(2)
	v_cmp_gt_u32_e64 s[4:5], s37, v1
	v_cndmask_b32_e32 v6, 0, v6, vcc
	v_mul_f32_e32 v7, v6, v12
	v_mul_f32_e32 v12, v6, v27
	v_mul_f32_e32 v27, v6, v36
	v_mul_f32_e32 v30, v6, v37
	v_rndne_f32_e32 v7, v7
	v_rndne_f32_e32 v12, v12
	v_mul_f32_e32 v31, v6, v38
	v_mul_f32_e32 v32, v6, v39
	v_mul_f32_e32 v34, v6, v41
	v_rndne_f32_e32 v27, v27
	v_rndne_f32_e32 v30, v30
	v_cvt_i32_f32_e32 v7, v7
	v_cvt_i32_f32_e32 v12, v12
	v_mul_f32_e32 v33, v6, v40
	v_rndne_f32_e32 v31, v31
	v_rndne_f32_e32 v32, v32
	v_rndne_f32_e32 v34, v34
	v_cvt_i32_f32_e32 v27, v27
	v_cvt_i32_f32_e32 v30, v30
	v_rndne_f32_e32 v33, v33
	v_cvt_i32_f32_e32 v31, v31
	v_cvt_i32_f32_e32 v32, v32
	v_cvt_i32_f32_e32 v34, v34
	v_cvt_i32_f32_e32 v33, v33
	v_add_u32_e32 v36, 8, v7
	v_add_u32_e32 v37, 8, v12
	v_and_b32_e32 v7, 15, v7
	v_lshlrev_b32_e32 v12, 4, v12
	v_lshl_add_u32 v38, v27, 4, v122
	v_lshlrev_b32_e32 v27, 8, v27
	v_lshl_add_u32 v39, v30, 8, v123
	v_lshrrev_b32_e32 v36, 4, v36
	v_and_b32_e32 v37, 0xf0, v37
	v_lshl_add_u32 v40, v31, 12, v124
	v_lshl_add_u32 v41, v32, 16, v125
	v_lshl_add_u32 v49, v34, 24, v127
	v_and_b32_e32 v12, 0xf0, v12
	v_and_b32_e32 v38, 0xf00, v38
	v_and_b32_e32 v27, 0xf00, v27
	v_and_b32_e32 v39, 0xf000, v39
	v_lshl_or_b32 v7, v34, 28, v7
	v_and_or_b32 v34, v36, 15, v37
	v_mul_f32_e32 v35, v6, v42
	v_lshlrev_b32_e32 v30, 12, v30
	v_lshlrev_b32_e32 v31, 16, v31
	v_lshl_add_u32 v42, v33, 20, v126
	v_and_b32_e32 v40, 0xf0000, v40
	v_and_b32_e32 v41, 0xf00000, v41
	v_or3_b32 v7, v7, v12, v27
	v_or3_b32 v12, v34, v38, v39
	v_and_b32_e32 v30, 0xf000, v30
	v_and_b32_e32 v31, 0xf0000, v31
	v_and_b32_e32 v42, 0xf000000, v42
	v_and_b32_e32 v49, 0xf0000000, v49
	v_or3_b32 v12, v12, v40, v41
	v_lshlrev_b32_e32 v32, 20, v32
	v_lshlrev_b32_e32 v33, 24, v33
	v_or3_b32 v7, v7, v30, v31
	v_or3_b32 v30, v12, v42, v49
	v_mul_f32_e32 v12, v6, v43
	v_rndne_f32_e32 v35, v35
	v_and_b32_e32 v32, 0xf00000, v32
	v_and_b32_e32 v33, 0xf000000, v33
	v_rndne_f32_e32 v12, v12
	v_or3_b32 v31, v7, v32, v33
	v_cvt_i32_f32_e32 v7, v35
	v_cvt_i32_f32_e32 v12, v12
	v_mul_f32_e32 v33, v6, v44
	v_mul_f32_e32 v5, v6, v5
	v_rndne_f32_e32 v33, v33
	v_rndne_f32_e32 v5, v5
	v_cvt_i32_f32_e32 v33, v33
	v_cvt_i32_f32_e32 v5, v5
	v_add_u32_e32 v27, 8, v7
	v_add_u32_e32 v32, 8, v12
	v_lshrrev_b32_e32 v27, 4, v27
	v_and_b32_e32 v32, 0xf0, v32
	v_and_or_b32 v27, v27, 15, v32
	v_lshl_add_u32 v32, v33, 4, v122
	v_lshl_add_u32 v34, v5, 8, v123
	v_and_b32_e32 v32, 0xf00, v32
	v_and_b32_e32 v34, 0xf000, v34
	v_mul_f32_e32 v35, v6, v45
	v_or3_b32 v27, v27, v32, v34
	v_mul_f32_e32 v34, v6, v46
	v_rndne_f32_e32 v35, v35
	v_rndne_f32_e32 v34, v34
	v_cvt_i32_f32_e32 v35, v35
	v_cvt_i32_f32_e32 v34, v34
	v_mul_f32_e32 v37, v6, v47
	v_mul_f32_e32 v6, v6, v48
	v_rndne_f32_e32 v37, v37
	v_rndne_f32_e32 v6, v6
	v_cvt_i32_f32_e32 v37, v37
	v_cvt_i32_f32_e32 v6, v6
	v_lshl_add_u32 v32, v35, 12, v124
	v_lshl_add_u32 v36, v34, 16, v125
	v_and_b32_e32 v32, 0xf0000, v32
	v_and_b32_e32 v36, 0xf00000, v36
	v_and_b32_e32 v7, 15, v7
	v_lshlrev_b32_e32 v12, 4, v12
	v_lshlrev_b32_e32 v33, 8, v33
	v_or3_b32 v27, v27, v32, v36
	v_lshlrev_b32_e32 v32, 20, v34
	v_and_b32_e32 v12, 0xf0, v12
	v_and_b32_e32 v33, 0xf00, v33
	v_lshlrev_b32_e32 v5, 12, v5
	v_lshlrev_b32_e32 v35, 16, v35
	v_and_b32_e32 v34, 0xf00000, v32
	v_lshl_add_u32 v32, v37, 20, v126
	v_lshlrev_b32_e32 v36, 24, v37
	v_lshl_add_u32 v37, v6, 24, v127
	v_lshl_or_b32 v6, v6, 28, v7
	v_and_b32_e32 v5, 0xf000, v5
	v_and_b32_e32 v35, 0xf0000, v35
	v_or3_b32 v6, v6, v12, v33
	v_and_b32_e32 v32, 0xf000000, v32
	v_and_b32_e32 v36, 0xf000000, v36
	v_and_b32_e32 v37, 0xf0000000, v37
	v_or3_b32 v5, v6, v5, v35
	v_cmp_gt_u32_e32 vcc, s37, v4
	v_or3_b32 v32, v27, v32, v37
	v_or3_b32 v33, v5, v34, v36
	s_bcnt1_i32_b64 s8, vcc
	v_mov_b32_e32 v5, v13
	ds_write_b128 v128, v[30:33] offset:1024
	s_and_saveexec_b64 s[6:7], s[4:5]
	v_mbcnt_lo_u32_b32 v5, s4, 0
	v_mbcnt_hi_u32_b32 v5, s5, v5
	v_add_u32_e32 v5, s8, v5
	s_or_b64 exec, exec, s[6:7]
	v_ashrrev_i32_e32 v6, 11, v4
	s_bcnt1_i32_b64 s42, s[4:5]
	v_cmp_eq_u32_e64 s[4:5], 1, v6
	v_ashrrev_i32_e32 v7, 11, v1
	s_add_i32 s42, s42, s8
	s_bcnt1_i32_b64 s8, s[4:5]
	v_cmp_eq_u32_e64 s[6:7], 1, v7
	s_add_i32 s43, s42, s8
	s_and_saveexec_b64 s[8:9], s[6:7]
; __device__ __forceinline__ float bf_lo(unsigned u) { return __uint_as_float(u << 16); }
; __device__ __forceinline__ float bf_hi(unsigned u) { return __uint_as_float(u & 0xffff0000u); }
; __device__ __forceinline__ void p3_token(const Params& p, int tok, int lane, unsigned* rec, float& sh, int& hs8) {
;     ...
;         const u32x4 a = *(const u32x4*)(H + (size_t)tok * DM + lane * 16), b = *(const u32x4*)(H + (size_t)tok * DM + lane * 16 + 8);
;         const unsigned hw[8] = {a.x, a.y, a.z, a.w, b.x, b.y, b.z, b.w};
;         float hv[16];
;         float mx = 0.f;
; #pragma unroll
;         for (int i = 0; i < 8; i++) { hv[2 * i] = bf_lo(hw[i]); hv[2 * i + 1] = bf_hi(hw[i]); mx = fmaxf(mx, fmaxf(fabsf(hv[2 * i]), fabsf(hv[2 * i + 1]))); }
;         mx = wave_max(mx);
;     ...
; #pragma unroll
;     for (int v = 0; v < 8; v++) {
;         const unsigned long long m0 = __ballot(k0 == v), m1 = __ballot(k1 == v);
;         const int c0 = __popcll(m0);
;         const int r0 = __builtin_amdgcn_mbcnt_hi((unsigned)(m0 >> 32), __builtin_amdgcn_mbcnt_lo((unsigned)m0, 0u));
;         const int r1 = __builtin_amdgcn_mbcnt_hi((unsigned)(m1 >> 32), __builtin_amdgcn_mbcnt_lo((unsigned)m1, 0u));
;         pos0 = (k0 == v) ? base + r0 : pos0;
;         pos1 = (k1 == v) ? base + c0 + r1 : pos1;
;         base += c0 + __popcll(m1);
;     }
;     const float* tsc = (const float*)(p.ws + OFF_UB + 33554432);
;     const f32x2 s0 = *(const f32x2*)(tsc + 2 * e0), s1 = *(const f32x2*)(tsc + 2 * e1);
;     rec[pos0] = (unsigned)e0; rec[pos1] = (unsigned)e1;
;     rec[128 + pos0] = __float_as_uint(g0 * s0[1]); rec[128 + pos1] = __float_as_uint(g1 * s1[1]);
;     rec[512 + pos0] = __float_as_uint(sh * s0[0]); rec[512 + pos1] = __float_as_uint(sh * s1[0]);
	v_mbcnt_lo_u32_b32 v5, s6, 0
	v_mbcnt_hi_u32_b32 v5, s7, v5
	v_add_u32_e32 v5, s43, v5
	s_or_b64 exec, exec, s[8:9]
	s_bcnt1_i32_b64 s6, s[6:7]
	s_add_i32 s43, s43, s6
	v_cmp_eq_u32_e64 s[6:7], 2, v6
	s_bcnt1_i32_b64 s10, s[6:7]
	v_cmp_eq_u32_e64 s[8:9], 2, v7
	s_add_i32 s44, s43, s10
	s_and_saveexec_b64 s[10:11], s[8:9]
	v_mbcnt_lo_u32_b32 v5, s8, 0
	v_mbcnt_hi_u32_b32 v5, s9, v5
	v_add_u32_e32 v5, s44, v5
	s_or_b64 exec, exec, s[10:11]
	s_bcnt1_i32_b64 s8, s[8:9]
	s_add_i32 s44, s44, s8
	v_cmp_eq_u32_e64 s[8:9], 3, v6
	s_bcnt1_i32_b64 s12, s[8:9]
	v_cmp_eq_u32_e64 s[10:11], 3, v7
	s_add_i32 s45, s44, s12
	s_and_saveexec_b64 s[12:13], s[10:11]
	v_mbcnt_lo_u32_b32 v5, s10, 0
	v_mbcnt_hi_u32_b32 v5, s11, v5
	v_add_u32_e32 v5, s45, v5
	s_or_b64 exec, exec, s[12:13]
	s_bcnt1_i32_b64 s10, s[10:11]
	s_add_i32 s45, s45, s10
	v_cmp_eq_u32_e64 s[10:11], 4, v6
	s_bcnt1_i32_b64 s14, s[10:11]
	v_cmp_eq_u32_e64 s[12:13], 4, v7
	s_add_i32 s46, s45, s14
	s_and_saveexec_b64 s[14:15], s[12:13]
	v_mbcnt_lo_u32_b32 v5, s12, 0
	v_mbcnt_hi_u32_b32 v5, s13, v5
	v_add_u32_e32 v5, s46, v5
	s_or_b64 exec, exec, s[14:15]
	s_bcnt1_i32_b64 s12, s[12:13]
	s_add_i32 s46, s46, s12
	v_cmp_eq_u32_e64 s[12:13], 5, v6
	s_bcnt1_i32_b64 s16, s[12:13]
	v_cmp_eq_u32_e64 s[14:15], 5, v7
	s_add_i32 s47, s46, s16
	s_and_saveexec_b64 s[16:17], s[14:15]
	v_mbcnt_lo_u32_b32 v5, s14, 0
	v_mbcnt_hi_u32_b32 v5, s15, v5
	v_add_u32_e32 v5, s47, v5
	s_or_b64 exec, exec, s[16:17]
	s_bcnt1_i32_b64 s14, s[14:15]
	s_add_i32 s47, s47, s14
	v_cmp_eq_u32_e64 s[14:15], 6, v6
	s_bcnt1_i32_b64 s18, s[14:15]
	v_cmp_eq_u32_e64 s[16:17], 6, v7
	s_add_i32 s48, s47, s18
	s_and_saveexec_b64 s[18:19], s[16:17]
	v_mbcnt_lo_u32_b32 v5, s16, 0
	v_mbcnt_hi_u32_b32 v5, s17, v5
	v_add_u32_e32 v5, s48, v5
	s_or_b64 exec, exec, s[18:19]
	s_bcnt1_i32_b64 s16, s[16:17]
	s_add_i32 s48, s48, s16
	v_cmp_eq_u32_e64 s[16:17], 7, v6
	v_cmp_eq_u32_e64 s[18:19], 7, v7
	s_and_saveexec_b64 s[34:35], s[18:19]
	s_bcnt1_i32_b64 s49, s[16:17]
	v_mbcnt_lo_u32_b32 v5, s18, 0
	s_add_i32 s49, s48, s49
	v_mbcnt_hi_u32_b32 v5, s19, v5
	v_add_u32_e32 v5, s49, v5
	s_or_b64 exec, exec, s[34:35]
	v_or_b32_e32 v30, 1, v8
	v_ashrrev_i32_e32 v31, 31, v30
	v_lshlrev_b64 v[32:33], 11, v[30:31]
	v_lshl_add_u64 v[6:7], v[20:21], 0, v[32:33]
	global_load_dwordx4 v[34:37], v[6:7], off
	global_load_dwordx4 v[38:41], v[6:7], off offset:16
	v_mbcnt_lo_u32_b32 v7, s16, 0
	v_lshlrev_b32_e32 v6, 1, v4
	v_mbcnt_lo_u32_b32 v43, s12, 0
	v_lshlrev_b32_e32 v42, 1, v1
	v_mbcnt_hi_u32_b32 v51, s17, v7
	v_ashrrev_i32_e32 v7, 31, v6
	v_mbcnt_lo_u32_b32 v44, s10, 0
	v_mbcnt_lo_u32_b32 v45, s8, 0
	v_mbcnt_hi_u32_b32 v52, s13, v43
	v_ashrrev_i32_e32 v43, 31, v42
	v_lshl_add_u64 v[6:7], v[6:7], 2, s[26:27]
	v_mbcnt_hi_u32_b32 v53, s11, v44
	v_mbcnt_hi_u32_b32 v54, s9, v45
	v_lshl_add_u64 v[42:43], v[42:43], 2, s[26:27]
	global_load_dwordx2 v[44:45], v[6:7], off
	global_load_dwordx2 v[46:47], v[42:43], off
	v_mbcnt_lo_u32_b32 v48, s6, 0
	v_mbcnt_lo_u32_b32 v49, s4, 0
	v_mbcnt_lo_u32_b32 v50, vcc_lo, 0
	v_mbcnt_hi_u32_b32 v6, s7, v48
	v_mbcnt_hi_u32_b32 v7, s5, v49
	v_mbcnt_hi_u32_b32 v42, vcc_hi, v50
	v_add_u32_e32 v43, s48, v51
	v_add_u32_e32 v7, s42, v7
	v_cndmask_b32_e32 v42, 0, v42, vcc
	v_add_u32_e32 v6, s43, v6
	v_cndmask_b32_e64 v7, v42, v7, s[4:5]
	v_cndmask_b32_e64 v6, v7, v6, s[6:7]
	v_mbcnt_lo_u32_b32 v27, s14, 0
	v_mbcnt_hi_u32_b32 v27, s15, v27
	v_add_u32_e32 v27, s47, v27
	v_lshl_add_u32 v5, v5, 2, v11
	v_mul_f32_e32 v12, 0x3c09ae41, v0
	v_mov_b32_e32 v0, 0
	s_waitcnt vmcnt(3)
	v_lshlrev_b32_e32 v48, 16, v34
	v_and_b32_e32 v34, 0xffff0000, v34
	v_lshlrev_b32_e32 v49, 16, v35
	v_and_b32_e32 v35, 0xffff0000, v35
	v_lshlrev_b32_e32 v50, 16, v36
	v_and_b32_e32 v36, 0xffff0000, v36
	v_lshlrev_b32_e32 v51, 16, v37
	v_and_b32_e32 v55, 0xffff0000, v37
	s_waitcnt vmcnt(2)
	v_lshlrev_b32_e32 v56, 16, v38
	v_and_b32_e32 v57, 0xffff0000, v38
	v_lshlrev_b32_e32 v58, 16, v39
	v_and_b32_e32 v59, 0xffff0000, v39
	v_max_f32_e64 v37, |v34|, |v34|
	v_max_f32_e64 v38, |v48|, |v48|
	v_max_f32_e64 v39, |v35|, |v35|
	v_max_f32_e64 v62, |v49|, |v49|
	v_max_f32_e64 v63, |v36|, |v36|
	v_max_f32_e64 v64, |v50|, |v50|
	v_max_f32_e64 v65, |v55|, |v55|
	v_max_f32_e64 v66, |v51|, |v51|
	v_max_f32_e32 v37, v38, v37
	v_max_f32_e32 v38, v62, v39
	v_lshlrev_b32_e32 v60, 16, v40
	v_and_b32_e32 v40, 0xffff0000, v40
	v_lshlrev_b32_e32 v61, 16, v41
	v_and_b32_e32 v41, 0xffff0000, v41
	v_max_f32_e64 v67, |v57|, |v57|
	v_max_f32_e64 v68, |v56|, |v56|
	v_max_f32_e64 v69, |v59|, |v59|
	v_max_f32_e64 v70, |v58|, |v58|
	v_max_f32_e32 v39, v64, v63
	v_max_f32_e32 v62, v66, v65
	v_max3_f32 v37, v37, 0, v38
	v_max_f32_e64 v71, |v40|, |v40|
	v_max_f32_e64 v72, |v60|, |v60|
	v_max_f32_e64 v73, |v41|, |v41|
	v_max_f32_e64 v74, |v61|, |v61|
	v_max_f32_e32 v63, v68, v67
	v_max_f32_e32 v64, v70, v69
	v_max3_f32 v37, v37, v39, v62
	v_max_f32_e32 v65, v72, v71
	v_max_f32_e32 v66, v74, v73
	v_max3_f32 v37, v37, v63, v64
	v_max3_f32 v37, v37, v65, v66
	ds_bpermute_b32 v38, v112, v37
	v_add_u32_e32 v39, s46, v52
	v_add_u32_e32 v52, s45, v53
	v_add_u32_e32 v53, s44, v54
	v_cndmask_b32_e64 v6, v6, v53, s[8:9]
	s_waitcnt lgkmcnt(0)
	v_max_f32_e32 v38, v38, v38
	v_max_f32_e32 v37, v37, v38
	ds_bpermute_b32 v38, v113, v37
	v_cndmask_b32_e64 v6, v6, v52, s[10:11]
	v_cndmask_b32_e64 v6, v6, v39, s[12:13]
	v_cndmask_b32_e64 v6, v6, v27, s[14:15]
	v_cndmask_b32_e64 v6, v6, v43, s[16:17]
	s_waitcnt lgkmcnt(0)
	v_max_f32_e32 v38, v38, v38
	v_max_f32_e32 v37, v37, v38
	ds_bpermute_b32 v38, v114, v37
	v_lshl_add_u32 v6, v6, 2, v11
	ds_write_b32 v6, v4
	ds_write_b32 v5, v1
	s_waitcnt vmcnt(1)
	v_mul_f32_e32 v1, v2, v45
	s_waitcnt lgkmcnt(2)
; __device__ __forceinline__ void p3_token(const Params& p, int tok, int lane, unsigned* rec, float& sh, int& hs8) {
;     ...
;         mx = wave_max(mx);
;         const float inv = mx > 0.f ? 119.f / mx : 0.f;
;         sh = mx * (1.f / 119.f);
;         unsigned qh[4] = {0u, 0u, 0u, 0u};
; #pragma unroll
;         for (int e = 0; e < 16; e++) {
;             const int qi = (int)rintf(hv[e] * inv);
;             const int hh = (qi + 8) >> 4, hl = qi - 16 * hh;
;             qh[(e >> 3) * 2] |= (unsigned)(hh & 15) << ((e & 7) * 4);
;             qh[(e >> 3) * 2 + 1] |= (unsigned)(hl & 15) << ((e & 7) * 4);
;         }
;         hs8 = 0;
;         *(u32x4*)(rec + 256 + lane * 4) = (u32x4){qh[0], qh[1], qh[2], qh[3]};
;     }
;     const int e0 = eidx[(size_t)tok * 128 + lane], e1 = eidx[(size_t)tok * 128 + 64 + lane];
;     const float g0 = gwp[(size_t)tok * 128 + lane], g1 = gwp[(size_t)tok * 128 + 64 + lane];
	v_max_f32_e32 v7, v38, v38
	v_max_f32_e32 v7, v37, v7
	ds_bpermute_b32 v37, v115, v7
	s_waitcnt vmcnt(0)
	v_mul_f32_e32 v2, v3, v47
	v_mul_f32_e32 v3, v12, v44
	ds_write_b32 v6, v1 offset:512
	ds_write_b32 v5, v2 offset:512
	ds_write_b32 v6, v3 offset:2048
	v_mul_f32_e32 v12, v12, v46
	s_waitcnt lgkmcnt(3)
	v_max_f32_e32 v4, v37, v37
	v_max_f32_e32 v4, v7, v4
	ds_bpermute_b32 v7, v116, v4
	ds_write_b32 v5, v12 offset:2048
	s_waitcnt lgkmcnt(1)
	v_max_f32_e32 v7, v7, v7
	v_max_f32_e32 v4, v4, v7
	ds_bpermute_b32 v7, v117, v4
	s_waitcnt lgkmcnt(0)
	v_max_f32_e32 v1, v7, v7
	v_max_f32_e32 v1, v4, v1
	v_div_scale_f32 v2, s[4:5], v1, v1, s33
	v_rcp_f32_e32 v3, v2
	v_div_scale_f32 v4, vcc, s33, v1, s33
	v_fma_f32 v5, -v2, v3, 1.0
	v_fmac_f32_e32 v3, v5, v3
	v_mul_f32_e32 v5, v4, v3
	v_fma_f32 v6, -v2, v5, v4
	v_fmac_f32_e32 v5, v6, v3
	v_fma_f32 v2, -v2, v5, v4
	v_div_fmas_f32 v2, v2, v3, v5
	v_div_fixup_f32 v2, v2, v1, s33
	v_cmp_lt_f32_e32 vcc, 0, v1
	s_nop 1
	v_cndmask_b32_e32 v12, 0, v2, vcc
	v_mul_f32_e32 v2, v12, v48
	v_mul_f32_e32 v3, v12, v34
	v_rndne_f32_e32 v2, v2
	v_rndne_f32_e32 v3, v3
	v_cvt_i32_f32_e32 v2, v2
	v_cvt_i32_f32_e32 v3, v3
	v_mul_f32_e32 v4, v12, v49
	v_mul_f32_e32 v5, v12, v35
	v_rndne_f32_e32 v4, v4
	v_add_u32_e32 v6, 8, v2
	v_and_b32_e32 v27, 15, v2
	v_add_u32_e32 v2, 8, v3
	v_lshlrev_b32_e32 v3, 4, v3
	v_cvt_i32_f32_e32 v4, v4
	v_and_b32_e32 v42, 0xf0, v3
	v_rndne_f32_e32 v3, v5
	v_cvt_i32_f32_e32 v3, v3
	v_lshl_add_u32 v7, v4, 4, v122
	v_lshlrev_b32_e32 v4, 8, v4
	v_lshrrev_b32_e32 v6, 4, v6
	v_and_b32_e32 v2, 0xf0, v2
	v_and_b32_e32 v43, 0xf00, v4
	v_lshl_add_u32 v4, v3, 8, v123
	v_and_or_b32 v2, v6, 15, v2
	v_and_b32_e32 v5, 0xf00, v7
	v_and_b32_e32 v4, 0xf000, v4
	v_mul_f32_e32 v6, v12, v50
	v_rndne_f32_e32 v6, v6
	v_or3_b32 v2, v2, v5, v4
	v_mul_f32_e32 v4, v12, v36
	v_cvt_i32_f32_e32 v6, v6
	v_rndne_f32_e32 v4, v4
	v_cvt_i32_f32_e32 v4, v4
	v_lshlrev_b32_e32 v3, 12, v3
	v_lshlrev_b32_e32 v5, 16, v6
	v_and_b32_e32 v44, 0xf000, v3
	v_lshl_add_u32 v3, v6, 12, v124
	v_and_b32_e32 v45, 0xf0000, v5
	v_lshl_add_u32 v5, v4, 16, v125
	v_and_b32_e32 v3, 0xf0000, v3
	v_and_b32_e32 v5, 0xf00000, v5
	v_or3_b32 v46, v2, v3, v5
	v_lshlrev_b32_e32 v2, 20, v4
	v_and_b32_e32 v47, 0xf00000, v2
	v_mul_f32_e32 v2, v12, v51
	v_rndne_f32_e32 v2, v2
	v_cvt_i32_f32_e32 v48, v2
	v_lshlrev_b64 v[2:3], 9, v[30:31]
	v_lshl_or_b32 v2, v10, 2, v2
	v_lshl_add_u64 v[6:7], s[20:21], 0, v[2:3]
	v_or_b32_e32 v4, 0x100, v2
	v_mov_b32_e32 v5, v3
	v_lshl_add_u64 v[34:35], s[20:21], 0, v[4:5]
	v_lshl_add_u64 v[36:37], s[24:25], 0, v[2:3]
	v_lshl_add_u64 v[38:39], s[24:25], 0, v[4:5]
	global_load_dword v2, v[6:7], off
	global_load_dword v3, v[34:35], off
	global_load_dword v4, v[36:37], off
	global_load_dword v5, v[38:39], off
	v_mul_f32_e32 v7, v12, v55
	v_rndne_f32_e32 v7, v7
	v_cvt_i32_f32_e32 v7, v7
	v_lshlrev_b32_e32 v34, 24, v48
	v_lshl_add_u32 v6, v48, 20, v126
	v_and_b32_e32 v35, 0xf000000, v34
	v_lshl_add_u32 v34, v7, 24, v127
	v_and_b32_e32 v6, 0xf000000, v6
	v_and_b32_e32 v34, 0xf0000000, v34
	v_or3_b32 v34, v46, v6, v34
	v_lshl_or_b32 v6, v7, 28, v27
	v_or3_b32 v6, v6, v42, v43
	v_or3_b32 v6, v6, v44, v45
	v_or3_b32 v35, v6, v47, v35
	v_mul_f32_e32 v6, v12, v56
	v_mul_f32_e32 v7, v12, v57
	v_rndne_f32_e32 v6, v6
	v_rndne_f32_e32 v7, v7
	v_cvt_i32_f32_e32 v6, v6
	v_cvt_i32_f32_e32 v7, v7
	v_mul_f32_e32 v37, v12, v58
	v_mul_f32_e32 v38, v12, v59
	v_rndne_f32_e32 v37, v37
	v_rndne_f32_e32 v38, v38
	v_cvt_i32_f32_e32 v37, v37
	v_cvt_i32_f32_e32 v38, v38
	v_add_u32_e32 v27, 8, v6
	v_add_u32_e32 v36, 8, v7
	v_lshrrev_b32_e32 v27, 4, v27
	v_and_b32_e32 v36, 0xf0, v36
	v_and_or_b32 v27, v27, 15, v36
	v_lshl_add_u32 v36, v37, 4, v122
	v_lshl_add_u32 v39, v38, 8, v123
	v_and_b32_e32 v36, 0xf00, v36
	v_and_b32_e32 v39, 0xf000, v39
	v_mul_f32_e32 v42, v12, v60
	v_or3_b32 v27, v27, v36, v39
	v_mul_f32_e32 v39, v12, v40
	v_rndne_f32_e32 v42, v42
	v_rndne_f32_e32 v39, v39
	v_cvt_i32_f32_e32 v42, v42
	v_cvt_i32_f32_e32 v39, v39
	v_mul_f32_e32 v43, v12, v61
	v_mul_f32_e32 v12, v12, v41
	v_rndne_f32_e32 v12, v12
	v_rndne_f32_e32 v43, v43
	v_cvt_i32_f32_e32 v12, v12
	v_lshlrev_b32_e32 v36, 12, v38
	v_cvt_i32_f32_e32 v43, v43
	v_and_b32_e32 v38, 0xf000, v36
	v_lshl_add_u32 v36, v42, 12, v124
	v_lshlrev_b32_e32 v40, 16, v42
	v_lshl_add_u32 v42, v39, 16, v125
	v_and_b32_e32 v6, 15, v6
	v_lshlrev_b32_e32 v7, 4, v7
	v_lshlrev_b32_e32 v37, 8, v37
	v_and_b32_e32 v36, 0xf0000, v36
	v_and_b32_e32 v42, 0xf00000, v42
	v_and_b32_e32 v7, 0xf0, v7
	v_and_b32_e32 v37, 0xf00, v37
	v_or3_b32 v27, v27, v36, v42
	v_lshlrev_b32_e32 v36, 20, v39
	v_lshl_or_b32 v6, v12, 28, v6
	v_and_b32_e32 v40, 0xf0000, v40
	v_and_b32_e32 v39, 0xf00000, v36
	v_lshl_add_u32 v36, v43, 20, v126
	v_lshlrev_b32_e32 v41, 24, v43
	v_lshl_add_u32 v42, v12, 24, v127
	v_or3_b32 v6, v6, v7, v37
	v_and_b32_e32 v36, 0xf000000, v36
	v_and_b32_e32 v41, 0xf000000, v41
	v_and_b32_e32 v42, 0xf0000000, v42
	v_or3_b32 v6, v6, v38, v40
	v_or3_b32 v36, v27, v36, v42
	v_or3_b32 v37, v6, v39, v41
	ds_write_b128 v128, v[34:37] offset:3584
	s_waitcnt vmcnt(3)
	v_cmp_gt_u32_e32 vcc, s37, v2
	s_waitcnt vmcnt(2)
; __device__ __forceinline__ void p3_token(const Params& p, int tok, int lane, unsigned* rec, float& sh, int& hs8) {
;     ...
; #pragma unroll
;     for (int v = 0; v < 8; v++) {
;         const unsigned long long m0 = __ballot(k0 == v), m1 = __ballot(k1 == v);
;         const int c0 = __popcll(m0);
;         const int r0 = __builtin_amdgcn_mbcnt_hi((unsigned)(m0 >> 32), __builtin_amdgcn_mbcnt_lo((unsigned)m0, 0u));
;         const int r1 = __builtin_amdgcn_mbcnt_hi((unsigned)(m1 >> 32), __builtin_amdgcn_mbcnt_lo((unsigned)m1, 0u));
;         pos0 = (k0 == v) ? base + r0 : pos0;
;         pos1 = (k1 == v) ? base + c0 + r1 : pos1;
;         base += c0 + __popcll(m1);
;     }
;     const float* tsc = (const float*)(p.ws + OFF_UB + 33554432);
;     const f32x2 s0 = *(const f32x2*)(tsc + 2 * e0), s1 = *(const f32x2*)(tsc + 2 * e1);
;     rec[pos0] = (unsigned)e0; rec[pos1] = (unsigned)e1;
;     rec[128 + pos0] = __float_as_uint(g0 * s0[1]); rec[128 + pos1] = __float_as_uint(g1 * s1[1]);
;     rec[512 + pos0] = __float_as_uint(sh * s0[0]); rec[512 + pos1] = __float_as_uint(sh * s1[0]);
; }
	v_cmp_gt_u32_e64 s[4:5], s37, v3
	s_bcnt1_i32_b64 s8, vcc
	s_and_saveexec_b64 s[6:7], s[4:5]
	v_mbcnt_lo_u32_b32 v0, s4, 0
	v_mbcnt_hi_u32_b32 v0, s5, v0
	v_add_u32_e32 v0, s8, v0
	s_or_b64 exec, exec, s[6:7]
	v_ashrrev_i32_e32 v6, 11, v2
	s_bcnt1_i32_b64 s42, s[4:5]
	v_cmp_eq_u32_e64 s[4:5], 1, v6
	v_ashrrev_i32_e32 v7, 11, v3
	s_add_i32 s42, s42, s8
	s_bcnt1_i32_b64 s8, s[4:5]
	v_cmp_eq_u32_e64 s[6:7], 1, v7
	s_add_i32 s43, s42, s8
	s_and_saveexec_b64 s[8:9], s[6:7]
	v_mbcnt_lo_u32_b32 v0, s6, 0
	v_mbcnt_hi_u32_b32 v0, s7, v0
	v_add_u32_e32 v0, s43, v0
	s_or_b64 exec, exec, s[8:9]
	s_bcnt1_i32_b64 s6, s[6:7]
	s_add_i32 s43, s43, s6
	v_cmp_eq_u32_e64 s[6:7], 2, v6
	s_bcnt1_i32_b64 s10, s[6:7]
	v_cmp_eq_u32_e64 s[8:9], 2, v7
	s_add_i32 s44, s43, s10
	s_and_saveexec_b64 s[10:11], s[8:9]
	v_mbcnt_lo_u32_b32 v0, s8, 0
	v_mbcnt_hi_u32_b32 v0, s9, v0
	v_add_u32_e32 v0, s44, v0
	s_or_b64 exec, exec, s[10:11]
	s_bcnt1_i32_b64 s8, s[8:9]
	s_add_i32 s44, s44, s8
	v_cmp_eq_u32_e64 s[8:9], 3, v6
	s_bcnt1_i32_b64 s12, s[8:9]
	v_cmp_eq_u32_e64 s[10:11], 3, v7
	s_add_i32 s45, s44, s12
	s_and_saveexec_b64 s[12:13], s[10:11]
	v_mbcnt_lo_u32_b32 v0, s10, 0
	v_mbcnt_hi_u32_b32 v0, s11, v0
	v_add_u32_e32 v0, s45, v0
	s_or_b64 exec, exec, s[12:13]
	s_bcnt1_i32_b64 s10, s[10:11]
	s_add_i32 s45, s45, s10
	v_cmp_eq_u32_e64 s[10:11], 4, v6
	s_bcnt1_i32_b64 s14, s[10:11]
	v_cmp_eq_u32_e64 s[12:13], 4, v7
	s_add_i32 s46, s45, s14
	s_and_saveexec_b64 s[14:15], s[12:13]
	v_mbcnt_lo_u32_b32 v0, s12, 0
	v_mbcnt_hi_u32_b32 v0, s13, v0
	v_add_u32_e32 v0, s46, v0
	s_or_b64 exec, exec, s[14:15]
	s_bcnt1_i32_b64 s12, s[12:13]
	s_add_i32 s46, s46, s12
	v_cmp_eq_u32_e64 s[12:13], 5, v6
	s_bcnt1_i32_b64 s16, s[12:13]
	v_cmp_eq_u32_e64 s[14:15], 5, v7
	s_add_i32 s47, s46, s16
	s_and_saveexec_b64 s[16:17], s[14:15]
	v_mbcnt_lo_u32_b32 v0, s14, 0
	v_mbcnt_hi_u32_b32 v0, s15, v0
	v_add_u32_e32 v0, s47, v0
	s_or_b64 exec, exec, s[16:17]
	s_bcnt1_i32_b64 s14, s[14:15]
	s_add_i32 s47, s47, s14
	v_cmp_eq_u32_e64 s[14:15], 6, v6
	s_bcnt1_i32_b64 s18, s[14:15]
	v_cmp_eq_u32_e64 s[16:17], 6, v7
	s_add_i32 s48, s47, s18
	s_and_saveexec_b64 s[18:19], s[16:17]
	v_mbcnt_lo_u32_b32 v0, s16, 0
	v_mbcnt_hi_u32_b32 v0, s17, v0
	v_add_u32_e32 v0, s48, v0
	s_or_b64 exec, exec, s[18:19]
	s_bcnt1_i32_b64 s16, s[16:17]
	s_add_i32 s48, s48, s16
	v_cmp_eq_u32_e64 s[16:17], 7, v6
	v_cmp_eq_u32_e64 s[18:19], 7, v7
	s_and_saveexec_b64 s[34:35], s[18:19]
	s_bcnt1_i32_b64 s49, s[16:17]
	v_mbcnt_lo_u32_b32 v0, s18, 0
	s_add_i32 s49, s48, s49
	v_mbcnt_hi_u32_b32 v0, s19, v0
	v_add_u32_e32 v0, s49, v0
	s_or_b64 exec, exec, s[34:35]
	v_lshlrev_b32_e32 v6, 1, v2
	v_ashrrev_i32_e32 v7, 31, v6
	v_lshlrev_b32_e32 v34, 1, v3
	v_lshl_add_u64 v[6:7], v[6:7], 2, s[26:27]
	v_ashrrev_i32_e32 v35, 31, v34
	v_lshl_add_u64 v[34:35], v[34:35], 2, s[26:27]
	global_load_dwordx2 v[36:37], v[6:7], off
	global_load_dwordx2 v[38:39], v[34:35], off
	v_mbcnt_lo_u32_b32 v41, s4, 0
	v_mbcnt_lo_u32_b32 v42, vcc_lo, 0
	v_mbcnt_lo_u32_b32 v40, s6, 0
	v_mbcnt_hi_u32_b32 v41, s5, v41
	v_mbcnt_hi_u32_b32 v42, vcc_hi, v42
	v_mbcnt_lo_u32_b32 v34, s8, 0
	v_mbcnt_hi_u32_b32 v40, s7, v40
	v_add_u32_e32 v41, s42, v41
	v_cndmask_b32_e32 v42, 0, v42, vcc
	v_mbcnt_lo_u32_b32 v27, s10, 0
	v_mbcnt_hi_u32_b32 v34, s9, v34
	v_add_u32_e32 v40, s43, v40
	v_cndmask_b32_e64 v41, v42, v41, s[4:5]
	v_mbcnt_lo_u32_b32 v12, s12, 0
	v_mbcnt_hi_u32_b32 v27, s11, v27
	v_add_u32_e32 v34, s44, v34
	v_cndmask_b32_e64 v40, v41, v40, s[6:7]
	v_mbcnt_lo_u32_b32 v7, s14, 0
	v_mbcnt_hi_u32_b32 v12, s13, v12
	v_add_u32_e32 v27, s45, v27
	v_cndmask_b32_e64 v34, v40, v34, s[8:9]
	v_mbcnt_lo_u32_b32 v6, s16, 0
	v_mbcnt_hi_u32_b32 v7, s15, v7
	v_add_u32_e32 v12, s46, v12
	v_cndmask_b32_e64 v27, v34, v27, s[10:11]
	v_mbcnt_hi_u32_b32 v6, s17, v6
	v_add_u32_e32 v7, s47, v7
	v_cndmask_b32_e64 v12, v27, v12, s[12:13]
	v_add_u32_e32 v6, s48, v6
	v_cndmask_b32_e64 v7, v12, v7, s[14:15]
	v_cndmask_b32_e64 v6, v7, v6, s[16:17]
	v_mul_f32_e32 v1, 0x3c09ae41, v1
	v_lshl_add_u32 v6, v6, 2, v11
	v_lshl_add_u32 v0, v0, 2, v11
	ds_write_b32 v6, v2 offset:2560
	ds_write_b32 v0, v3 offset:2560
	v_mov_b32_e32 v35, v13
	v_mov_b32_e32 v41, v13
	s_mov_b32 s5, 0
	s_waitcnt vmcnt(1)
	v_mul_f32_e32 v2, v4, v37
	s_waitcnt vmcnt(0)
	v_mul_f32_e32 v3, v5, v39
	v_mul_f32_e32 v4, v1, v36
	v_mul_f32_e32 v1, v1, v38
	ds_write_b32 v6, v2 offset:3072
	ds_write_b32 v0, v3 offset:3072
	ds_write_b32 v6, v4 offset:4608
	ds_write_b32 v0, v1 offset:4608
	ds_read_b128 v[0:3], v11
	ds_read_b128 v[4:7], v11 offset:2560
	v_mov_b32_e32 v37, v13
	v_mov_b32_e32 v39, v13
	s_waitcnt lgkmcnt(1)
	v_mov_b32_e32 v12, v0
	v_mov_b32_e32 v34, v1
	v_mov_b32_e32 v36, v3
	s_waitcnt lgkmcnt(0)
; template <int CTRL> __device__ __forceinline__ int dpp_i(int v) { return __builtin_amdgcn_mov_dpp(v, CTRL, 0xF, 0xF, true); }
; __device__ __forceinline__ void p3_load_u(u32x2 (&ur)[4], P3Sc& sc, const unsigned char* __restrict__ UQ, const float* __restrict__ tsc,
;                                           int lane, int ul, int g, const unsigned* rec) {
; #pragma unroll
;     for (int u = 0; u < 4; u++) ur[u] = *(const u32x2*)(UQ + (size_t)rec[4 * g + u] * 512 + lane * 8);
;     sc.gm = __uint_as_float(rec[128 + 4 * g + ul]);
;     sc.su = __uint_as_float(rec[512 + 4 * g + ul]);
;     sc.sv = 1.f;
; }
; __device__ __forceinline__ void p3_load_v(u32x2 (&vr)[4], const unsigned char* __restrict__ VQ, int lane, int g, const unsigned* rec) {
; #pragma unroll
;     for (int u = 0; u < 4; u++) vr[u] = *(const u32x2*)(VQ + (size_t)rec[4 * g + u] * 512 + lane * 8);
; }
; __device__ __forceinline__ void p3_dots(const u32x2 (&ur)[4], const unsigned* rec, int lane, int (&pt)[4]) {
;     const u32x4 qh = *(const u32x4*)(rec + 256 + lane * 4);
; #pragma unroll
;     for (int u = 0; u < 4; u++) {
;         const int w0 = (int)ur[u].x, w1 = (int)ur[u].y;
;         int dh = __builtin_amdgcn_sdot8(w0, (int)qh.x, 0, false);
;         dh = __builtin_amdgcn_sdot8(w1, (int)qh.z, dh, false);
;         int dl = __builtin_amdgcn_sdot8(w0, (int)qh.y, 0, false);
;         dl = __builtin_amdgcn_sdot8(w1, (int)qh.w, dl, false);
;         pt[u] = (dh << 4) + dl;
;     }
; }
; __device__ __forceinline__ float p3_weight(const int (&pt)[4], int lane, float sh, int hs8, const P3Sc& sc) {
;     int m2[2], m1;
;     const bool c0 = lane & 1;
; #pragma unroll
;     for (int j = 0; j < 2; j++) { const int keep = c0 ? pt[j + 2] : pt[j], send = c0 ? pt[j] : pt[j + 2]; m2[j] = keep + dpp_i<0xB1>(send); }
;     const bool c1 = lane & 2;
;     { const int keep = c1 ? m2[1] : m2[0], send = c1 ? m2[0] : m2[1]; m1 = keep + dpp_i<0x4E>(send); }
	v_mov_b32_e32 v38, v5
	v_mov_b32_e32 v40, v7
	v_lshlrev_b64 v[0:1], 9, v[34:35]
	v_lshlrev_b64 v[34:35], 9, v[12:13]
	v_mov_b32_e32 v12, v2
	v_lshlrev_b64 v[2:3], 9, v[36:37]
	v_lshlrev_b64 v[36:37], 9, v[38:39]
	v_lshlrev_b64 v[38:39], 9, v[40:41]
	v_lshl_add_u64 v[40:41], v[14:15], 0, v[34:35]
	v_lshlrev_b64 v[44:45], 9, v[12:13]
	v_lshl_add_u64 v[42:43], v[14:15], 0, v[0:1]
	v_lshl_add_u64 v[46:47], v[14:15], 0, v[2:3]
	v_lshl_add_u64 v[34:35], v[16:17], 0, v[34:35]
	v_lshl_add_u64 v[0:1], v[16:17], 0, v[0:1]
	v_lshl_add_u64 v[2:3], v[16:17], 0, v[2:3]
	v_mov_b32_e32 v12, v4
	v_lshl_add_u64 v[50:51], v[14:15], 0, v[44:45]
	v_lshl_add_u64 v[44:45], v[16:17], 0, v[44:45]
	global_load_dwordx2 v[80:81], v[40:41], off
	global_load_dwordx2 v[74:75], v[42:43], off
	global_load_dwordx2 v[84:85], v[50:51], off
	global_load_dwordx2 v[82:83], v[46:47], off
	global_load_dwordx2 v[72:73], v[34:35], off
	global_load_dwordx2 v[70:71], v[0:1], off
	global_load_dwordx2 v[62:63], v[44:45], off
	global_load_dwordx2 v[58:59], v[2:3], off
	v_lshlrev_b64 v[52:53], 9, v[12:13]
	v_mov_b32_e32 v12, v6
	v_lshl_add_u64 v[0:1], v[14:15], 0, v[52:53]
	v_lshlrev_b64 v[2:3], 9, v[12:13]
	v_lshl_add_u64 v[4:5], v[14:15], 0, v[36:37]
	v_lshl_add_u64 v[48:49], v[14:15], 0, v[38:39]
	v_lshl_add_u64 v[6:7], v[14:15], 0, v[2:3]
	global_load_dwordx2 v[66:67], v[0:1], off
	global_load_dwordx2 v[60:61], v[4:5], off
	global_load_dwordx2 v[68:69], v[6:7], off
	global_load_dwordx2 v[64:65], v[48:49], off
	v_lshl_add_u64 v[0:1], v[16:17], 0, v[52:53]
	v_lshl_add_u64 v[4:5], v[16:17], 0, v[36:37]
	v_lshl_add_u64 v[2:3], v[16:17], 0, v[2:3]
	v_lshl_add_u64 v[6:7], v[16:17], 0, v[38:39]
	global_load_dwordx2 v[40:41], v[0:1], off
	global_load_dwordx2 v[38:39], v[4:5], off
	global_load_dwordx2 v[36:37], v[2:3], off
	global_load_dwordx2 v[34:35], v[6:7], off
	ds_read2st64_b32 v[76:77], v119 offset0:2 offset1:8
	ds_read2st64_b32 v[78:79], v119 offset0:12 offset1:18
	ds_read_b128 v[4:7], v128 offset:1024
	ds_read_b128 v[0:3], v128 offset:3584
	v_mov_b32_e32 v42, 0
	v_mov_b32_e32 v43, v42
	v_mov_b32_e32 v44, v42
	v_mov_b32_e32 v45, v42
	v_mov_b32_e32 v46, v42
	v_mov_b32_e32 v47, v42
	v_mov_b32_e32 v48, v42
	v_mov_b32_e32 v49, v42
	v_mov_b32_e32 v50, v42
	v_mov_b32_e32 v51, v42
	v_mov_b32_e32 v52, v42
	v_mov_b32_e32 v53, v42
	v_mov_b32_e32 v86, v42
	v_mov_b32_e32 v87, v42
	v_mov_b32_e32 v88, v42
	v_mov_b32_e32 v89, v42
	v_mov_b32_e32 v90, v42
	v_mov_b32_e32 v91, v42
	v_mov_b32_e32 v92, v42
	v_mov_b32_e32 v93, v42
	v_mov_b32_e32 v94, v42
	v_mov_b32_e32 v95, v42
	v_mov_b32_e32 v96, v42
	v_mov_b32_e32 v97, v42
	v_mov_b32_e32 v98, v42
	v_mov_b32_e32 v99, v42
	v_mov_b32_e32 v100, v42
	v_mov_b32_e32 v101, v42
	v_mov_b32_e32 v54, v42
	v_mov_b32_e32 v55, v42
	v_mov_b32_e32 v56, v42
	v_mov_b32_e32 v57, v42
	s_waitcnt vmcnt(0)
	ds_write_b64 v149, v[80:81]
	ds_write_b64 v149, v[74:75] offset:512
	ds_write_b64 v149, v[84:85] offset:1024
	ds_write_b64 v149, v[82:83] offset:1536
	ds_write_b64 v149, v[66:67] offset:2048
	ds_write_b64 v149, v[60:61] offset:2560
	ds_write_b64 v149, v[68:69] offset:3072
	ds_write_b64 v149, v[64:65] offset:3584
	ds_read_b128 v[184:187], v154
	ds_read_b128 v[188:191], v154 offset:1024
	ds_read_b128 v[192:195], v154 offset:2048
	ds_read_b128 v[196:199], v154 offset:3072
	v_and_b32_e32 v155, 31, v159
	v_lshlrev_b32_e32 v155, 5, v155
	v_lshlrev_b32_e32 v156, 4, v159
	v_sub_u32_e32 v155, v155, v156
	v_add_u32_e32 v155, v128, v155
	ds_read_b128 v[224:227], v155 offset:1024
	ds_read_b128 v[228:231], v155 offset:1040
	ds_read_b128 v[232:235], v155 offset:3584
	ds_read_b128 v[236:239], v155 offset:3600
	s_waitcnt lgkmcnt(0)
	v_cndmask_b32_e64 v76, v76, v78, s[54:55]
	v_cndmask_b32_e64 v77, v77, v79, s[54:55]
	.p2alignl 6, 3212836864
.LBB0_1075:
	v_add_u32_e32 v134, s5, v121
	v_add_u32_e32 v135, s5, v137
	ds_read_b128 v[140:143], v134
	ds_read_b128 v[144:147], v134 offset:2560
	s_waitcnt vmcnt(10) lgkmcnt(2)
	v_dot8_i32_i4 v12, v184, v224, 0
	v_dot8_i32_i4 v27, v184, v225, 0
	v_dot8_i32_i4 v133, v188, v224, 0
	v_dot8_i32_i4 v177, v188, v225, 0
	v_dot8c_i32_i4_e32 v12, v185, v226
	v_dot8c_i32_i4_e32 v27, v185, v227
	v_dot8c_i32_i4_e32 v133, v189, v226
	v_dot8c_i32_i4_e32 v177, v189, v227
	v_dot8c_i32_i4_e32 v12, v186, v228
	v_dot8c_i32_i4_e32 v27, v186, v229
	v_dot8c_i32_i4_e32 v133, v190, v228
	v_dot8c_i32_i4_e32 v177, v190, v229
	v_dot8c_i32_i4_e32 v12, v187, v230
	v_dot8c_i32_i4_e32 v27, v187, v231
	v_dot8c_i32_i4_e32 v133, v191, v230
	v_dot8c_i32_i4_e32 v177, v191, v231
	s_nop 0
	v_lshl_add_u32 v176, v12, 4, v27
	v_cndmask_b32_e64 v27, 0, v176, s[58:59]
	v_cndmask_b32_e64 v131, v176, 0, s[58:59]
	v_lshl_add_u32 v178, v133, 4, v177
	v_cndmask_b32_e64 v132, 0, v178, s[58:59]
	v_cndmask_b32_e64 v133, v178, 0, s[58:59]
	v_cndmask_b32_e64 v12, v132, v27, s[0:1]
	v_cndmask_b32_e64 v27, v27, v132, s[0:1]
	s_waitcnt lgkmcnt(0)
	v_cndmask_b32_e64 v150, v141, v140, s[58:59]
	v_add_u32_dpp v12, v27, v12 quad_perm:[1,0,3,2] row_mask:0xf bank_mask:0xf bound_ctrl:1
	v_cndmask_b32_e64 v27, v133, v131, s[0:1]
	v_cndmask_b32_e64 v131, v131, v133, s[0:1]
	v_cndmask_b32_e64 v151, v143, v142, s[58:59]
	v_lshl_add_u32 v150, v150, 9, v148
	v_add_u32_dpp v27, v131, v27 quad_perm:[1,0,3,2] row_mask:0xf bank_mask:0xf bound_ctrl:1
	v_cndmask_b32_e64 v131, v27, v12, s[2:3]
	v_cndmask_b32_e64 v12, v12, v27, s[2:3]
	v_lshl_add_u32 v151, v151, 9, v148
	global_load_dwordx4 v[184:187], v150, s[50:51]
	v_add_u32_dpp v12, v12, v131 quad_perm:[2,3,0,1] row_mask:0xf bank_mask:0xf bound_ctrl:1
	global_load_dwordx4 v[188:191], v151, s[50:51]
	v_lshl_add_u32 v140, v140, 9, v136
	v_add_u32_dpp v12, v12, v12 row_ror:4 row_mask:0xf bank_mask:0xf bound_ctrl:1
	v_lshl_add_u32 v141, v141, 9, v136
	s_waitcnt vmcnt(6)
; __device__ __forceinline__ void p3_dots(const u32x2 (&ur)[4], const unsigned* rec, int lane, int (&pt)[4]) {
;     const u32x4 qh = *(const u32x4*)(rec + 256 + lane * 4);
; #pragma unroll
;     for (int u = 0; u < 4; u++) {
;         const int w0 = (int)ur[u].x, w1 = (int)ur[u].y;
;         int dh = __builtin_amdgcn_sdot8(w0, (int)qh.x, 0, false);
;         dh = __builtin_amdgcn_sdot8(w1, (int)qh.z, dh, false);
;         int dl = __builtin_amdgcn_sdot8(w0, (int)qh.y, 0, false);
;         dl = __builtin_amdgcn_sdot8(w1, (int)qh.w, dl, false);
;         pt[u] = (dh << 4) + dl;
;     }
; }
; template <int CTRL> __device__ __forceinline__ int dpp_i(int v) { return __builtin_amdgcn_mov_dpp(v, CTRL, 0xF, 0xF, true); }
; __device__ __forceinline__ int xrow_sum_i(int v) {
;     const auto a = __builtin_amdgcn_permlane16_swap((unsigned)v, (unsigned)v, false, false);
;     v = (int)a[0] + (int)a[1];
;     const auto b = __builtin_amdgcn_permlane32_swap((unsigned)v, (unsigned)v, false, false);
;     return (int)b[0] + (int)b[1];
; }
; __device__ __forceinline__ float p3_weight(const int (&pt)[4], int lane, float sh, int hs8, const P3Sc& sc) {
;     int m2[2], m1;
;     const bool c0 = lane & 1;
; #pragma unroll
;     for (int j = 0; j < 2; j++) { const int keep = c0 ? pt[j + 2] : pt[j], send = c0 ? pt[j] : pt[j + 2]; m2[j] = keep + dpp_i<0xB1>(send); }
;     const bool c1 = lane & 2;
;     { const int keep = c1 ? m2[1] : m2[0], send = c1 ? m2[0] : m2[1]; m1 = keep + dpp_i<0x4E>(send); }
;     m1 += dpp_i<0x124>(m1);
;     m1 += dpp_i<0x128>(m1);
;     m1 = xrow_sum_i(m1);
;     const float aval = (float)(m1 - hs8) * sc.su;
;     return sc.gm * gelu_erf(aval);
; }
; __device__ __forceinline__ void p3_axpy(const u32x2 (&vr)[4], float ws, f32x2 (&acc)[8]) {
; #pragma unroll
;     for (int u = 0; u < 4; u++) {
;         const int la = ((u >> 1) & 1) | ((u & 1) << 1);
;         const float wu = __builtin_bit_cast(float, __builtin_amdgcn_readlane(__builtin_bit_cast(int, ws), la));
;         const f32x2 w2 = {wu, wu};
;         const unsigned vw[2] = {vr[u].x, vr[u].y};
; #pragma unroll
;         for (int i = 0; i < 2; i++) {
;             acc[i * 4 + 0] = __builtin_elementwise_fma(w2, __builtin_amdgcn_cvt_scalef32_pk_f32_fp4(vw[i], 1.0f, 0), acc[i * 4 + 0]);
	v_add_u32_dpp v181, v12, v12 row_ror:8 row_mask:0xf bank_mask:0xf bound_ctrl:1
	v_lshl_add_u32 v142, v142, 9, v136
	v_lshl_add_u32 v143, v143, 9, v136
	v_cndmask_b32_e64 v152, v145, v144, s[58:59]
	v_cndmask_b32_e64 v153, v147, v146, s[58:59]
	v_lshl_add_u32 v152, v152, 9, v148
	v_lshl_add_u32 v153, v153, 9, v148
	v_dot8_i32_i4 v12, v192, v232, 0
	v_dot8_i32_i4 v27, v192, v233, 0
	v_dot8_i32_i4 v133, v196, v232, 0
	v_dot8_i32_i4 v177, v196, v233, 0
	v_dot8c_i32_i4_e32 v12, v193, v234
	v_dot8c_i32_i4_e32 v27, v193, v235
	v_dot8c_i32_i4_e32 v133, v197, v234
	v_dot8c_i32_i4_e32 v177, v197, v235
	v_dot8c_i32_i4_e32 v12, v194, v236
	v_dot8c_i32_i4_e32 v27, v194, v237
	v_dot8c_i32_i4_e32 v133, v198, v236
	v_dot8c_i32_i4_e32 v177, v198, v237
	v_dot8c_i32_i4_e32 v12, v195, v238
	v_dot8c_i32_i4_e32 v27, v195, v239
	v_dot8c_i32_i4_e32 v133, v199, v238
	v_dot8c_i32_i4_e32 v177, v199, v239
	s_nop 0
	v_lshl_add_u32 v176, v12, 4, v27
	v_cndmask_b32_e64 v27, 0, v176, s[58:59]
	v_cndmask_b32_e64 v131, v176, 0, s[58:59]
	v_lshl_add_u32 v178, v133, 4, v177
	v_cndmask_b32_e64 v132, 0, v178, s[58:59]
	v_cndmask_b32_e64 v133, v178, 0, s[58:59]
	v_cndmask_b32_e64 v12, v132, v27, s[0:1]
	v_cndmask_b32_e64 v27, v27, v132, s[0:1]
	v_lshl_add_u32 v144, v144, 9, v136
	v_lshl_add_u32 v145, v145, 9, v136
	v_add_u32_dpp v12, v27, v12 quad_perm:[1,0,3,2] row_mask:0xf bank_mask:0xf bound_ctrl:1
	v_cndmask_b32_e64 v27, v133, v131, s[0:1]
	v_cndmask_b32_e64 v131, v131, v133, s[0:1]
	v_lshl_add_u32 v146, v146, 9, v136
	v_lshl_add_u32 v147, v147, 9, v136
	v_add_u32_dpp v27, v131, v27 quad_perm:[1,0,3,2] row_mask:0xf bank_mask:0xf bound_ctrl:1
	v_cndmask_b32_e64 v131, v27, v12, s[2:3]
	v_cndmask_b32_e64 v12, v12, v27, s[2:3]
	global_load_dwordx4 v[192:195], v152, s[50:51]
	global_load_dwordx4 v[196:199], v153, s[50:51]
	v_add_u32_dpp v12, v12, v131 quad_perm:[2,3,0,1] row_mask:0xf bank_mask:0xf bound_ctrl:1
	v_cvt_scalef32_pk_f32_fp4 v[160:161], v72, 1.0
	v_cvt_scalef32_pk_f32_fp4 v[162:163], v72, 1.0 op_sel:[1,0,0]
	v_add_u32_dpp v12, v12, v12 row_ror:4 row_mask:0xf bank_mask:0xf bound_ctrl:1
	s_nop 0
	s_nop 0
	v_add_u32_dpp v12, v12, v12 row_ror:8 row_mask:0xf bank_mask:0xf bound_ctrl:1
	v_cvt_scalef32_pk_f32_fp4 v[164:165], v72, 1.0 op_sel:[0,1,0]
	v_cvt_scalef32_pk_f32_fp4 v[166:167], v72, 1.0 op_sel:[1,1,0]
	v_permlane16_swap_b32_e32 v181, v12
	v_add_u32_e32 v12, v181, v12
	v_mov_b32_e32 v27, v12
	v_cvt_scalef32_pk_f32_fp4 v[168:169], v73, 1.0
	v_cvt_scalef32_pk_f32_fp4 v[170:171], v73, 1.0 op_sel:[1,0,0]
	v_permlane32_swap_b32_e32 v12, v27
	v_add_u32_e32 v12, v27, v12
	v_cvt_f32_i32_e32 v12, v12
	v_mul_f32_e32 v12, v77, v12
	v_fma_f32 v179, |v12|, s39, 1.0
	v_rcp_f32_e32 v179, v179
	v_cmp_gt_f32_e32 vcc, 0, v12
	v_fmamk_f32 v180, v179, 0x3f07dc22, v129
	v_fmaak_f32 v180, v179, v180, 0x3f35f0e3
	v_fmaak_f32 v180, v179, v180, 0xbe11a98e
	v_fmaak_f32 v180, v179, v180, 0x3e027906
	v_mul_f32_e32 v179, v179, v180
	v_mul_f32_e32 v180, v12, v12
	v_mul_f32_e32 v180, 0xbf38aa3b, v180
	v_exp_f32_e32 v180, v180
	v_cvt_scalef32_pk_f32_fp4 v[172:173], v73, 1.0 op_sel:[0,1,0]
	v_mul_f32_e32 v179, v180, v179
	v_mul_f32_e32 v180, v12, v179
	v_fma_f32 v12, -v12, v179, v12
	v_cndmask_b32_e32 v12, v12, v180, vcc
	v_mul_f32_e32 v12, v76, v12
	ds_read2st64_b32 v[76:77], v135 offset1:6
	v_readlane_b32 s4, v12, 0
	v_cvt_scalef32_pk_f32_fp4 v[174:175], v73, 1.0 op_sel:[1,1,0]
	global_load_dwordx2 v[72:73], v140, s[52:53]
	v_pk_fma_f32 v[100:101], s[4:5], v[160:161], v[100:101] op_sel_hi:[0,1,1]
	v_pk_fma_f32 v[98:99], s[4:5], v[162:163], v[98:99] op_sel_hi:[0,1,1]
	v_pk_fma_f32 v[96:97], s[4:5], v[164:165], v[96:97] op_sel_hi:[0,1,1]
	v_pk_fma_f32 v[94:95], s[4:5], v[166:167], v[94:95] op_sel_hi:[0,1,1]
	v_pk_fma_f32 v[92:93], s[4:5], v[168:169], v[92:93] op_sel_hi:[0,1,1]
	v_pk_fma_f32 v[90:91], s[4:5], v[170:171], v[90:91] op_sel_hi:[0,1,1]
	v_pk_fma_f32 v[88:89], s[4:5], v[172:173], v[88:89] op_sel_hi:[0,1,1]
	v_pk_fma_f32 v[86:87], s[4:5], v[174:175], v[86:87] op_sel_hi:[0,1,1]
	v_readlane_b32 s4, v12, 2
	v_cvt_scalef32_pk_f32_fp4 v[160:161], v70, 1.0
	v_cvt_scalef32_pk_f32_fp4 v[162:163], v70, 1.0 op_sel:[1,0,0]
	v_pk_fma_f32 v[100:101], s[4:5], v[160:161], v[100:101] op_sel_hi:[0,1,1]
	v_cvt_scalef32_pk_f32_fp4 v[164:165], v70, 1.0 op_sel:[0,1,0]
	v_pk_fma_f32 v[98:99], s[4:5], v[162:163], v[98:99] op_sel_hi:[0,1,1]
	v_cvt_scalef32_pk_f32_fp4 v[166:167], v70, 1.0 op_sel:[1,1,0]
	v_pk_fma_f32 v[96:97], s[4:5], v[164:165], v[96:97] op_sel_hi:[0,1,1]
	v_cvt_scalef32_pk_f32_fp4 v[168:169], v71, 1.0
	v_pk_fma_f32 v[94:95], s[4:5], v[166:167], v[94:95] op_sel_hi:[0,1,1]
	v_cvt_scalef32_pk_f32_fp4 v[170:171], v71, 1.0 op_sel:[1,0,0]
	v_pk_fma_f32 v[92:93], s[4:5], v[168:169], v[92:93] op_sel_hi:[0,1,1]
	v_cvt_scalef32_pk_f32_fp4 v[172:173], v71, 1.0 op_sel:[0,1,0]
	v_pk_fma_f32 v[90:91], s[4:5], v[170:171], v[90:91] op_sel_hi:[0,1,1]
	v_cvt_scalef32_pk_f32_fp4 v[174:175], v71, 1.0 op_sel:[1,1,0]
	v_pk_fma_f32 v[88:89], s[4:5], v[172:173], v[88:89] op_sel_hi:[0,1,1]
	v_pk_fma_f32 v[86:87], s[4:5], v[174:175], v[86:87] op_sel_hi:[0,1,1]
	global_load_dwordx2 v[70:71], v141, s[52:53]
	v_readlane_b32 s4, v12, 1
	v_cvt_scalef32_pk_f32_fp4 v[160:161], v62, 1.0
	v_cvt_scalef32_pk_f32_fp4 v[162:163], v62, 1.0 op_sel:[1,0,0]
	v_pk_fma_f32 v[100:101], s[4:5], v[160:161], v[100:101] op_sel_hi:[0,1,1]
	v_cvt_scalef32_pk_f32_fp4 v[164:165], v62, 1.0 op_sel:[0,1,0]
	v_pk_fma_f32 v[98:99], s[4:5], v[162:163], v[98:99] op_sel_hi:[0,1,1]
	v_cvt_scalef32_pk_f32_fp4 v[166:167], v62, 1.0 op_sel:[1,1,0]
	v_pk_fma_f32 v[96:97], s[4:5], v[164:165], v[96:97] op_sel_hi:[0,1,1]
	v_cvt_scalef32_pk_f32_fp4 v[168:169], v63, 1.0
; __device__ __forceinline__ void p3_axpy(const u32x2 (&vr)[4], float ws, f32x2 (&acc)[8]) {
; #pragma unroll
;     for (int u = 0; u < 4; u++) {
;         const int la = ((u >> 1) & 1) | ((u & 1) << 1);
;         const float wu = __builtin_bit_cast(float, __builtin_amdgcn_readlane(__builtin_bit_cast(int, ws), la));
;         const f32x2 w2 = {wu, wu};
;         const unsigned vw[2] = {vr[u].x, vr[u].y};
; #pragma unroll
;         for (int i = 0; i < 2; i++) {
;             acc[i * 4 + 0] = __builtin_elementwise_fma(w2, __builtin_amdgcn_cvt_scalef32_pk_f32_fp4(vw[i], 1.0f, 0), acc[i * 4 + 0]);
;             acc[i * 4 + 1] = __builtin_elementwise_fma(w2, __builtin_amdgcn_cvt_scalef32_pk_f32_fp4(vw[i], 1.0f, 1), acc[i * 4 + 1]);
;             acc[i * 4 + 2] = __builtin_elementwise_fma(w2, __builtin_amdgcn_cvt_scalef32_pk_f32_fp4(vw[i], 1.0f, 2), acc[i * 4 + 2]);
;             acc[i * 4 + 3] = __builtin_elementwise_fma(w2, __builtin_amdgcn_cvt_scalef32_pk_f32_fp4(vw[i], 1.0f, 3), acc[i * 4 + 3]);
;         }
;     }
; }
; __device__ void phaseP3(const Params& p, float* dstp, char* lds) {
;     ...
;         for (int g = 0; g < 32; g++) {
; #pragma unroll
;             for (int k = 0; k < TPW; k++) {
;                 int pt[4];
;                 p3_dots(ur[k], recs + k * (P3_REC / 4), lane, pt);
;                 const P3Sc sck = sc[k];
;                 if (g + 1 < 32) p3_load_u(ur[k], sc[k], UQ, tsc, lane, ul, g + 1, recs + k * (P3_REC / 4));
;                 const float w = p3_weight(pt, lane, sh[k], hs8[k], sck);
;                 p3_axpy(vr[k], w, acc[k]);
;                 if (g + 1 < 32) p3_load_v(vr[k], VQ, lane, g + 1, recs + k * (P3_REC / 4));
;             }
	v_pk_fma_f32 v[94:95], s[4:5], v[166:167], v[94:95] op_sel_hi:[0,1,1]
	v_cvt_scalef32_pk_f32_fp4 v[170:171], v63, 1.0 op_sel:[1,0,0]
	v_pk_fma_f32 v[92:93], s[4:5], v[168:169], v[92:93] op_sel_hi:[0,1,1]
	v_cvt_scalef32_pk_f32_fp4 v[172:173], v63, 1.0 op_sel:[0,1,0]
	v_pk_fma_f32 v[90:91], s[4:5], v[170:171], v[90:91] op_sel_hi:[0,1,1]
	v_cvt_scalef32_pk_f32_fp4 v[174:175], v63, 1.0 op_sel:[1,1,0]
	v_pk_fma_f32 v[88:89], s[4:5], v[172:173], v[88:89] op_sel_hi:[0,1,1]
	v_pk_fma_f32 v[86:87], s[4:5], v[174:175], v[86:87] op_sel_hi:[0,1,1]
	global_load_dwordx2 v[62:63], v142, s[52:53]
	v_readlane_b32 s4, v12, 3
	v_cvt_scalef32_pk_f32_fp4 v[160:161], v58, 1.0
	v_cvt_scalef32_pk_f32_fp4 v[162:163], v58, 1.0 op_sel:[1,0,0]
	v_pk_fma_f32 v[100:101], s[4:5], v[160:161], v[100:101] op_sel_hi:[0,1,1]
	v_cvt_scalef32_pk_f32_fp4 v[164:165], v58, 1.0 op_sel:[0,1,0]
	v_pk_fma_f32 v[98:99], s[4:5], v[162:163], v[98:99] op_sel_hi:[0,1,1]
	v_cvt_scalef32_pk_f32_fp4 v[166:167], v58, 1.0 op_sel:[1,1,0]
	v_pk_fma_f32 v[96:97], s[4:5], v[164:165], v[96:97] op_sel_hi:[0,1,1]
	v_cvt_scalef32_pk_f32_fp4 v[168:169], v59, 1.0
	v_pk_fma_f32 v[94:95], s[4:5], v[166:167], v[94:95] op_sel_hi:[0,1,1]
	v_cvt_scalef32_pk_f32_fp4 v[170:171], v59, 1.0 op_sel:[1,0,0]
	v_pk_fma_f32 v[92:93], s[4:5], v[168:169], v[92:93] op_sel_hi:[0,1,1]
	v_cvt_scalef32_pk_f32_fp4 v[172:173], v59, 1.0 op_sel:[0,1,0]
	v_pk_fma_f32 v[90:91], s[4:5], v[170:171], v[90:91] op_sel_hi:[0,1,1]
	v_cvt_scalef32_pk_f32_fp4 v[174:175], v59, 1.0 op_sel:[1,1,0]
	v_pk_fma_f32 v[88:89], s[4:5], v[172:173], v[88:89] op_sel_hi:[0,1,1]
	v_pk_fma_f32 v[86:87], s[4:5], v[174:175], v[86:87] op_sel_hi:[0,1,1]
	global_load_dwordx2 v[58:59], v143, s[52:53]
	s_waitcnt vmcnt(11)
	v_readlane_b32 s4, v12, 16
	v_cvt_scalef32_pk_f32_fp4 v[160:161], v40, 1.0
	v_cvt_scalef32_pk_f32_fp4 v[162:163], v40, 1.0 op_sel:[1,0,0]
	v_pk_fma_f32 v[52:53], s[4:5], v[160:161], v[52:53] op_sel_hi:[0,1,1]
	v_cvt_scalef32_pk_f32_fp4 v[164:165], v40, 1.0 op_sel:[0,1,0]
	v_pk_fma_f32 v[50:51], s[4:5], v[162:163], v[50:51] op_sel_hi:[0,1,1]
	v_cvt_scalef32_pk_f32_fp4 v[166:167], v40, 1.0 op_sel:[1,1,0]
	v_pk_fma_f32 v[48:49], s[4:5], v[164:165], v[48:49] op_sel_hi:[0,1,1]
	v_cvt_scalef32_pk_f32_fp4 v[168:169], v41, 1.0
	v_pk_fma_f32 v[46:47], s[4:5], v[166:167], v[46:47] op_sel_hi:[0,1,1]
	v_cvt_scalef32_pk_f32_fp4 v[170:171], v41, 1.0 op_sel:[1,0,0]
	v_pk_fma_f32 v[44:45], s[4:5], v[168:169], v[44:45] op_sel_hi:[0,1,1]
	v_cvt_scalef32_pk_f32_fp4 v[172:173], v41, 1.0 op_sel:[0,1,0]
	v_pk_fma_f32 v[42:43], s[4:5], v[170:171], v[42:43] op_sel_hi:[0,1,1]
	v_cvt_scalef32_pk_f32_fp4 v[174:175], v41, 1.0 op_sel:[1,1,0]
	v_pk_fma_f32 v[54:55], s[4:5], v[172:173], v[54:55] op_sel_hi:[0,1,1]
	v_pk_fma_f32 v[56:57], s[4:5], v[174:175], v[56:57] op_sel_hi:[0,1,1]
	global_load_dwordx2 v[40:41], v144, s[52:53]
	s_waitcnt vmcnt(11)
	v_readlane_b32 s4, v12, 18
	v_cvt_scalef32_pk_f32_fp4 v[160:161], v38, 1.0
	v_cvt_scalef32_pk_f32_fp4 v[162:163], v38, 1.0 op_sel:[1,0,0]
	v_pk_fma_f32 v[52:53], s[4:5], v[160:161], v[52:53] op_sel_hi:[0,1,1]
	v_cvt_scalef32_pk_f32_fp4 v[164:165], v38, 1.0 op_sel:[0,1,0]
	v_pk_fma_f32 v[50:51], s[4:5], v[162:163], v[50:51] op_sel_hi:[0,1,1]
	v_cvt_scalef32_pk_f32_fp4 v[166:167], v38, 1.0 op_sel:[1,1,0]
	v_pk_fma_f32 v[48:49], s[4:5], v[164:165], v[48:49] op_sel_hi:[0,1,1]
	v_cvt_scalef32_pk_f32_fp4 v[168:169], v39, 1.0
	v_pk_fma_f32 v[46:47], s[4:5], v[166:167], v[46:47] op_sel_hi:[0,1,1]
	v_cvt_scalef32_pk_f32_fp4 v[170:171], v39, 1.0 op_sel:[1,0,0]
	v_pk_fma_f32 v[44:45], s[4:5], v[168:169], v[44:45] op_sel_hi:[0,1,1]
	v_cvt_scalef32_pk_f32_fp4 v[172:173], v39, 1.0 op_sel:[0,1,0]
	v_pk_fma_f32 v[42:43], s[4:5], v[170:171], v[42:43] op_sel_hi:[0,1,1]
	v_cvt_scalef32_pk_f32_fp4 v[174:175], v39, 1.0 op_sel:[1,1,0]
	v_pk_fma_f32 v[54:55], s[4:5], v[172:173], v[54:55] op_sel_hi:[0,1,1]
	v_pk_fma_f32 v[56:57], s[4:5], v[174:175], v[56:57] op_sel_hi:[0,1,1]
	global_load_dwordx2 v[38:39], v145, s[52:53]
	s_waitcnt vmcnt(11)
	v_readlane_b32 s4, v12, 17
	v_cvt_scalef32_pk_f32_fp4 v[160:161], v36, 1.0
	v_cvt_scalef32_pk_f32_fp4 v[162:163], v36, 1.0 op_sel:[1,0,0]
	v_pk_fma_f32 v[52:53], s[4:5], v[160:161], v[52:53] op_sel_hi:[0,1,1]
	v_cvt_scalef32_pk_f32_fp4 v[164:165], v36, 1.0 op_sel:[0,1,0]
	v_pk_fma_f32 v[50:51], s[4:5], v[162:163], v[50:51] op_sel_hi:[0,1,1]
	v_cvt_scalef32_pk_f32_fp4 v[166:167], v36, 1.0 op_sel:[1,1,0]
	v_pk_fma_f32 v[48:49], s[4:5], v[164:165], v[48:49] op_sel_hi:[0,1,1]
	v_cvt_scalef32_pk_f32_fp4 v[168:169], v37, 1.0
	v_pk_fma_f32 v[46:47], s[4:5], v[166:167], v[46:47] op_sel_hi:[0,1,1]
	v_cvt_scalef32_pk_f32_fp4 v[170:171], v37, 1.0 op_sel:[1,0,0]
	v_pk_fma_f32 v[44:45], s[4:5], v[168:169], v[44:45] op_sel_hi:[0,1,1]
	v_cvt_scalef32_pk_f32_fp4 v[172:173], v37, 1.0 op_sel:[0,1,0]
	v_pk_fma_f32 v[42:43], s[4:5], v[170:171], v[42:43] op_sel_hi:[0,1,1]
	v_cvt_scalef32_pk_f32_fp4 v[174:175], v37, 1.0 op_sel:[1,1,0]
	v_pk_fma_f32 v[54:55], s[4:5], v[172:173], v[54:55] op_sel_hi:[0,1,1]
	v_pk_fma_f32 v[56:57], s[4:5], v[174:175], v[56:57] op_sel_hi:[0,1,1]
	global_load_dwordx2 v[36:37], v146, s[52:53]
	s_waitcnt vmcnt(11)
	v_readlane_b32 s4, v12, 19
	v_cvt_scalef32_pk_f32_fp4 v[160:161], v34, 1.0
	v_cvt_scalef32_pk_f32_fp4 v[162:163], v34, 1.0 op_sel:[1,0,0]
	v_pk_fma_f32 v[52:53], s[4:5], v[160:161], v[52:53] op_sel_hi:[0,1,1]
	v_cvt_scalef32_pk_f32_fp4 v[164:165], v34, 1.0 op_sel:[0,1,0]
	v_pk_fma_f32 v[50:51], s[4:5], v[162:163], v[50:51] op_sel_hi:[0,1,1]
	v_cvt_scalef32_pk_f32_fp4 v[166:167], v34, 1.0 op_sel:[1,1,0]
	v_pk_fma_f32 v[48:49], s[4:5], v[164:165], v[48:49] op_sel_hi:[0,1,1]
	v_cvt_scalef32_pk_f32_fp4 v[168:169], v35, 1.0
	v_pk_fma_f32 v[46:47], s[4:5], v[166:167], v[46:47] op_sel_hi:[0,1,1]
	v_cvt_scalef32_pk_f32_fp4 v[170:171], v35, 1.0 op_sel:[1,0,0]
	v_pk_fma_f32 v[44:45], s[4:5], v[168:169], v[44:45] op_sel_hi:[0,1,1]
	v_cvt_scalef32_pk_f32_fp4 v[172:173], v35, 1.0 op_sel:[0,1,0]
	v_pk_fma_f32 v[42:43], s[4:5], v[170:171], v[42:43] op_sel_hi:[0,1,1]
	v_cvt_scalef32_pk_f32_fp4 v[174:175], v35, 1.0 op_sel:[1,1,0]
	v_pk_fma_f32 v[54:55], s[4:5], v[172:173], v[54:55] op_sel_hi:[0,1,1]
	v_pk_fma_f32 v[56:57], s[4:5], v[174:175], v[56:57] op_sel_hi:[0,1,1]
	global_load_dwordx2 v[34:35], v147, s[52:53]
	s_add_i32 s5, s5, 16
	s_cmpk_eq_i32 s5, 0x1f0
	s_cbranch_scc0 .LBB0_1075
; __device__ __forceinline__ void p3_dots(const u32x2 (&ur)[4], const unsigned* rec, int lane, int (&pt)[4]) {
;     const u32x4 qh = *(const u32x4*)(rec + 256 + lane * 4);
; #pragma unroll
;     for (int u = 0; u < 4; u++) {
;         const int w0 = (int)ur[u].x, w1 = (int)ur[u].y;
;         int dh = __builtin_amdgcn_sdot8(w0, (int)qh.x, 0, false);
;         dh = __builtin_amdgcn_sdot8(w1, (int)qh.z, dh, false);
;         int dl = __builtin_amdgcn_sdot8(w0, (int)qh.y, 0, false);
;         dl = __builtin_amdgcn_sdot8(w1, (int)qh.w, dl, false);
;         pt[u] = (dh << 4) + dl;
;     }
; }
; template <int CTRL> __device__ __forceinline__ int dpp_i(int v) { return __builtin_amdgcn_mov_dpp(v, CTRL, 0xF, 0xF, true); }
; __device__ __forceinline__ int xrow_sum_i(int v) {
;     const auto a = __builtin_amdgcn_permlane16_swap((unsigned)v, (unsigned)v, false, false);
;     v = (int)a[0] + (int)a[1];
;     const auto b = __builtin_amdgcn_permlane32_swap((unsigned)v, (unsigned)v, false, false);
;     return (int)b[0] + (int)b[1];
; }
; __device__ __forceinline__ float p3_weight(const int (&pt)[4], int lane, float sh, int hs8, const P3Sc& sc) {
;     int m2[2], m1;
;     const bool c0 = lane & 1;
; #pragma unroll
;     for (int j = 0; j < 2; j++) { const int keep = c0 ? pt[j + 2] : pt[j], send = c0 ? pt[j] : pt[j + 2]; m2[j] = keep + dpp_i<0xB1>(send); }
;     const bool c1 = lane & 2;
;     { const int keep = c1 ? m2[1] : m2[0], send = c1 ? m2[0] : m2[1]; m1 = keep + dpp_i<0x4E>(send); }
;     m1 += dpp_i<0x124>(m1);
;     m1 += dpp_i<0x128>(m1);
;     m1 = xrow_sum_i(m1);
;     const float aval = (float)(m1 - hs8) * sc.su;
;     return sc.gm * gelu_erf(aval);
; }
; __device__ __forceinline__ void p3_axpy(const u32x2 (&vr)[4], float ws, f32x2 (&acc)[8]) {
; #pragma unroll
;     for (int u = 0; u < 4; u++) {
;         const int la = ((u >> 1) & 1) | ((u & 1) << 1);
;         const float wu = __builtin_bit_cast(float, __builtin_amdgcn_readlane(__builtin_bit_cast(int, ws), la));
;         const f32x2 w2 = {wu, wu};
;         const unsigned vw[2] = {vr[u].x, vr[u].y};
; #pragma unroll
;         for (int i = 0; i < 2; i++) {
;             acc[i * 4 + 0] = __builtin_elementwise_fma(w2, __builtin_amdgcn_cvt_scalef32_pk_f32_fp4(vw[i], 1.0f, 0), acc[i * 4 + 0]);
	v_add_u32_e32 v135, 0x1e0, v120
	ds_read2st64_b32 v[104:105], v135 offset1:6
	ds_read2st64_b32 v[102:103], v135 offset0:10 offset1:16
	s_waitcnt vmcnt(0) lgkmcnt(0)
	ds_write_b128 v154, v[184:187]
	ds_write_b128 v154, v[188:191] offset:1024
	ds_write_b128 v154, v[192:195] offset:2048
	ds_write_b128 v154, v[196:199] offset:3072
	ds_read_b64 v[80:81], v149
	ds_read_b64 v[74:75], v149 offset:512
	ds_read_b64 v[84:85], v149 offset:1024
	ds_read_b64 v[82:83], v149 offset:1536
	ds_read_b64 v[66:67], v149 offset:2048
	ds_read_b64 v[60:61], v149 offset:2560
	ds_read_b64 v[68:69], v149 offset:3072
	ds_read_b64 v[64:65], v149 offset:3584
	s_waitcnt lgkmcnt(0)
	v_mov_b32_e32 v12, v13
	v_mov_b32_e32 v27, v13
	s_waitcnt vmcnt(8)
	v_dot8c_i32_i4_e32 v12, v82, v4
	v_dot8c_i32_i4_e32 v27, v82, v5
	v_dot8c_i32_i4_e32 v12, v83, v6
	v_dot8c_i32_i4_e32 v27, v83, v7
	v_mov_b32_e32 v76, v13
	v_dot8c_i32_i4_e32 v76, v84, v5
	v_dot8c_i32_i4_e32 v76, v85, v7
	v_lshl_add_u32 v12, v12, 4, v27
	v_mov_b32_e32 v27, v13
	v_dot8c_i32_i4_e32 v27, v84, v4
	v_dot8c_i32_i4_e32 v27, v85, v6
	v_mov_b32_e32 v77, v13
	v_dot8c_i32_i4_e32 v77, v74, v5
	v_dot8c_i32_i4_e32 v77, v75, v7
	v_lshl_add_u32 v27, v27, 4, v76
	v_mov_b32_e32 v76, v13
	v_dot8c_i32_i4_e32 v76, v74, v4
	v_dot8c_i32_i4_e32 v76, v75, v6
	v_mov_b32_e32 v75, v13
	v_dot8c_i32_i4_e32 v75, v80, v4
	v_mov_b32_e32 v4, v13
	v_dot8c_i32_i4_e32 v4, v80, v5
	v_dot8c_i32_i4_e32 v75, v81, v6
	v_dot8c_i32_i4_e32 v4, v81, v7
	v_lshl_add_u32 v74, v76, 4, v77
	v_cndmask_b32_e64 v6, v74, v12, s[0:1]
	v_cvt_scalef32_pk_f32_fp4 v[76:77], v72, 1.0 op_sel:[1,1,0]
	v_lshl_add_u32 v4, v75, 4, v4
	v_cndmask_b32_e64 v5, v27, v4, s[0:1]
	v_cndmask_b32_e64 v4, v4, v27, s[0:1]
	v_cvt_scalef32_pk_f32_fp4 v[78:79], v73, 1.0
	v_cvt_scalef32_pk_f32_fp4 v[80:81], v73, 1.0 op_sel:[1,0,0]
	v_add_u32_dpp v4, v4, v5 quad_perm:[1,0,3,2] row_mask:0xf bank_mask:0xf bound_ctrl:1
	v_cndmask_b32_e64 v5, v12, v74, s[0:1]
	v_cvt_scalef32_pk_f32_fp4 v[74:75], v72, 1.0 op_sel:[0,1,0]
	v_cvt_scalef32_pk_f32_fp4 v[82:83], v73, 1.0 op_sel:[0,1,0]
	v_add_u32_dpp v5, v6, v5 quad_perm:[1,0,3,2] row_mask:0xf bank_mask:0xf bound_ctrl:1
	v_cndmask_b32_e64 v6, v5, v4, s[2:3]
	v_cndmask_b32_e64 v4, v4, v5, s[2:3]
	v_cvt_scalef32_pk_f32_fp4 v[84:85], v70, 1.0
	v_lshl_add_u64 v[28:29], v[22:23], 0, v[28:29]
	v_add_u32_dpp v4, v4, v6 quad_perm:[2,3,0,1] row_mask:0xf bank_mask:0xf bound_ctrl:1
	v_mov_b32_e32 v27, v13
	v_cvt_scalef32_pk_f32_fp4 v[108:109], v62, 1.0 op_sel:[0,1,0]
	v_add_u32_dpp v4, v4, v4 row_ror:4 row_mask:0xf bank_mask:0xf bound_ctrl:1
	s_nop 1
	v_add_u32_dpp v4, v4, v4 row_ror:8 row_mask:0xf bank_mask:0xf bound_ctrl:1
	v_mov_b32_e32 v5, v4
	s_nop 1
	v_permlane16_swap_b32_e32 v4, v5
	v_add_u32_e32 v4, v4, v5
	v_mov_b32_e32 v5, v4
	s_nop 1
	v_permlane32_swap_b32_e32 v4, v5
	v_add_u32_e32 v4, v5, v4
	v_cvt_f32_i32_e32 v4, v4
	v_mul_f32_e32 v4, v105, v4
	v_fma_f32 v5, |v4|, s39, 1.0
	v_rcp_f32_e32 v5, v5
	v_mul_f32_e32 v7, v4, v4
	v_mul_f32_e32 v7, 0xbf38aa3b, v7
	v_exp_f32_e32 v7, v7
	v_fmamk_f32 v6, v5, 0x3f07dc22, v129
	v_fmaak_f32 v6, v5, v6, 0x3f35f0e3
	v_fmaak_f32 v6, v5, v6, 0xbe11a98e
	v_fmaak_f32 v6, v5, v6, 0x3e027906
	v_mul_f32_e32 v5, v5, v6
	v_mul_f32_e32 v5, v7, v5
	v_mul_f32_e32 v6, v4, v5
	v_fma_f32 v5, -v4, v5, v4
	v_cmp_gt_f32_e32 vcc, 0, v4
	s_nop 1
	v_cndmask_b32_e32 v4, v5, v6, vcc
	v_mul_f32_e32 v12, v104, v4
	v_cvt_scalef32_pk_f32_fp4 v[4:5], v72, 1.0
	v_readlane_b32 s4, v12, 0
	v_cvt_scalef32_pk_f32_fp4 v[6:7], v72, 1.0 op_sel:[1,0,0]
	v_cvt_scalef32_pk_f32_fp4 v[72:73], v73, 1.0 op_sel:[1,1,0]
	v_pk_fma_f32 v[4:5], s[4:5], v[4:5], v[100:101] op_sel_hi:[0,1,1]
	v_pk_fma_f32 v[6:7], s[4:5], v[6:7], v[98:99] op_sel_hi:[0,1,1]
	v_pk_fma_f32 v[74:75], s[4:5], v[74:75], v[96:97] op_sel_hi:[0,1,1]
	v_pk_fma_f32 v[76:77], s[4:5], v[76:77], v[94:95] op_sel_hi:[0,1,1]
	v_pk_fma_f32 v[78:79], s[4:5], v[78:79], v[92:93] op_sel_hi:[0,1,1]
	v_pk_fma_f32 v[80:81], s[4:5], v[80:81], v[90:91] op_sel_hi:[0,1,1]
	v_pk_fma_f32 v[82:83], s[4:5], v[82:83], v[88:89] op_sel_hi:[0,1,1]
	v_pk_fma_f32 v[72:73], s[4:5], v[72:73], v[86:87] op_sel_hi:[0,1,1]
	v_readlane_b32 s4, v12, 2
	s_nop 1
	v_pk_fma_f32 v[4:5], s[4:5], v[84:85], v[4:5] op_sel_hi:[0,1,1]
	v_cvt_scalef32_pk_f32_fp4 v[84:85], v70, 1.0 op_sel:[1,0,0]
	v_pk_fma_f32 v[84:85], s[4:5], v[84:85], v[6:7] op_sel_hi:[0,1,1]
	v_cvt_scalef32_pk_f32_fp4 v[6:7], v70, 1.0 op_sel:[0,1,0]
	v_pk_fma_f32 v[90:91], s[4:5], v[6:7], v[74:75] op_sel_hi:[0,1,1]
	v_cvt_scalef32_pk_f32_fp4 v[6:7], v70, 1.0 op_sel:[1,1,0]
	v_pk_fma_f32 v[92:93], s[4:5], v[6:7], v[76:77] op_sel_hi:[0,1,1]
	v_cvt_scalef32_pk_f32_fp4 v[6:7], v71, 1.0
	v_pk_fma_f32 v[94:95], s[4:5], v[6:7], v[78:79] op_sel_hi:[0,1,1]
	v_cvt_scalef32_pk_f32_fp4 v[6:7], v71, 1.0 op_sel:[1,0,0]
	v_pk_fma_f32 v[96:97], s[4:5], v[6:7], v[80:81] op_sel_hi:[0,1,1]
	v_cvt_scalef32_pk_f32_fp4 v[6:7], v71, 1.0 op_sel:[0,1,0]
	v_pk_fma_f32 v[98:99], s[4:5], v[6:7], v[82:83] op_sel_hi:[0,1,1]
	v_cvt_scalef32_pk_f32_fp4 v[6:7], v71, 1.0 op_sel:[1,1,0]
	v_pk_fma_f32 v[100:101], s[4:5], v[6:7], v[72:73] op_sel_hi:[0,1,1]
	v_ashrrev_i32_e32 v6, 11, v8
	v_mul_i32_i24_e32 v6, 0x1800, v6
	v_ashrrev_i32_e32 v7, 31, v6
	v_lshl_add_u64 v[6:7], v[6:7], 2, s[22:23]
	v_readlane_b32 s4, v12, 1
	global_load_dwordx4 v[70:73], v[28:29], off offset:16
	global_load_dwordx4 v[74:77], v[28:29], off
	v_lshl_add_u64 v[28:29], v[6:7], 0, v[26:27]
	v_cvt_scalef32_pk_f32_fp4 v[82:83], v62, 1.0
	v_add_co_u32_e32 v6, vcc, s40, v28
	v_pk_fma_f32 v[104:105], s[4:5], v[82:83], v[4:5] op_sel_hi:[0,1,1]
	v_cvt_scalef32_pk_f32_fp4 v[4:5], v62, 1.0 op_sel:[1,0,0]
	v_addc_co_u32_e32 v7, vcc, 0, v29, vcc
	v_pk_fma_f32 v[106:107], s[4:5], v[4:5], v[84:85] op_sel_hi:[0,1,1]
	v_lshl_add_u64 v[4:5], v[28:29], 0, s[30:31]
	v_pk_fma_f32 v[28:29], s[4:5], v[108:109], v[90:91] op_sel_hi:[0,1,1]
	v_cvt_scalef32_pk_f32_fp4 v[90:91], v62, 1.0 op_sel:[1,1,0]
	v_pk_fma_f32 v[108:109], s[4:5], v[90:91], v[92:93] op_sel_hi:[0,1,1]
	v_cvt_scalef32_pk_f32_fp4 v[90:91], v63, 1.0
	global_load_dwordx4 v[78:81], v[6:7], off
	v_pk_fma_f32 v[94:95], s[4:5], v[90:91], v[94:95] op_sel_hi:[0,1,1]
	v_cvt_scalef32_pk_f32_fp4 v[90:91], v63, 1.0 op_sel:[1,0,0]
	global_load_dwordx4 v[82:85], v[4:5], off offset:32
	global_load_dwordx4 v[86:89], v[4:5], off offset:16
	v_pk_fma_f32 v[96:97], s[4:5], v[90:91], v[96:97] op_sel_hi:[0,1,1]
	v_cvt_scalef32_pk_f32_fp4 v[90:91], v63, 1.0 op_sel:[0,1,0]
	v_cvt_scalef32_pk_f32_fp4 v[62:63], v63, 1.0 op_sel:[1,1,0]
	v_pk_fma_f32 v[98:99], s[4:5], v[90:91], v[98:99] op_sel_hi:[0,1,1]
	v_pk_fma_f32 v[62:63], s[4:5], v[62:63], v[100:101] op_sel_hi:[0,1,1]
	v_readlane_b32 s4, v12, 3
	s_waitcnt vmcnt(11)
; __device__ __forceinline__ void p3_dots(const u32x2 (&ur)[4], const unsigned* rec, int lane, int (&pt)[4]) {
;     const u32x4 qh = *(const u32x4*)(rec + 256 + lane * 4);
; #pragma unroll
;     for (int u = 0; u < 4; u++) {
;         const int w0 = (int)ur[u].x, w1 = (int)ur[u].y;
;         int dh = __builtin_amdgcn_sdot8(w0, (int)qh.x, 0, false);
;         dh = __builtin_amdgcn_sdot8(w1, (int)qh.z, dh, false);
;         int dl = __builtin_amdgcn_sdot8(w0, (int)qh.y, 0, false);
;         dl = __builtin_amdgcn_sdot8(w1, (int)qh.w, dl, false);
;         pt[u] = (dh << 4) + dl;
;     }
; }
; template <int CTRL> __device__ __forceinline__ int dpp_i(int v) { return __builtin_amdgcn_mov_dpp(v, CTRL, 0xF, 0xF, true); }
; __device__ __forceinline__ int xrow_sum_i(int v) {
;     const auto a = __builtin_amdgcn_permlane16_swap((unsigned)v, (unsigned)v, false, false);
;     v = (int)a[0] + (int)a[1];
;     const auto b = __builtin_amdgcn_permlane32_swap((unsigned)v, (unsigned)v, false, false);
;     return (int)b[0] + (int)b[1];
; }
; __device__ __forceinline__ float p3_weight(const int (&pt)[4], int lane, float sh, int hs8, const P3Sc& sc) {
;     int m2[2], m1;
;     const bool c0 = lane & 1;
; #pragma unroll
;     for (int j = 0; j < 2; j++) { const int keep = c0 ? pt[j + 2] : pt[j], send = c0 ? pt[j] : pt[j + 2]; m2[j] = keep + dpp_i<0xB1>(send); }
;     const bool c1 = lane & 2;
;     { const int keep = c1 ? m2[1] : m2[0], send = c1 ? m2[0] : m2[1]; m1 = keep + dpp_i<0x4E>(send); }
;     m1 += dpp_i<0x124>(m1);
;     m1 += dpp_i<0x128>(m1);
;     m1 = xrow_sum_i(m1);
;     const float aval = (float)(m1 - hs8) * sc.su;
;     return sc.gm * gelu_erf(aval);
; }
; __device__ __forceinline__ void p3_finish(const Params& p, float* dstp, int tok, int lane, const f32x2 (&acc)[8], float* tr) {
;     ...
;     const bf16_t* x1b = (const bf16_t*)(p.ws + OFF_X1B) + (size_t)tok * DM + d0;
;     const u32x4 xa = *(const u32x4*)x1b, xb = *(const u32x4*)(x1b + 8);
;     const unsigned xw[8] = {xa.x, xa.y, xa.z, xa.w, xb.x, xb.y, xb.z, xb.w};
; #pragma unroll
;     for (int i = 0; i < 4; i++) {
;         const int d = d0 + i * 4;
;         const f32x4 xv = {bf_lo(xw[2 * i]), bf_hi(xw[2 * i]), bf_lo(xw[2 * i + 1]), bf_hi(xw[2 * i + 1])};
;         const f32x4 gt = *(const f32x4*)(mod + b * 6144 + 5 * 1024 + d);
; #pragma unroll
	v_cvt_scalef32_pk_f32_fp4 v[90:91], v58, 1.0
	v_mov_b32_e32 v12, v13
	v_pk_fma_f32 v[100:101], s[4:5], v[90:91], v[104:105] op_sel_hi:[0,1,1]
	global_load_dwordx4 v[90:93], v[4:5], off offset:48
	v_cvt_scalef32_pk_f32_fp4 v[104:105], v58, 1.0 op_sel:[1,0,0]
	v_pk_fma_f32 v[104:105], s[4:5], v[104:105], v[106:107] op_sel_hi:[0,1,1]
	v_cvt_scalef32_pk_f32_fp4 v[106:107], v58, 1.0 op_sel:[0,1,0]
	v_pk_fma_f32 v[28:29], s[4:5], v[106:107], v[28:29] op_sel_hi:[0,1,1]
	v_cvt_scalef32_pk_f32_fp4 v[106:107], v58, 1.0 op_sel:[1,1,0]
	v_pk_fma_f32 v[106:107], s[4:5], v[106:107], v[108:109] op_sel_hi:[0,1,1]
	v_cvt_scalef32_pk_f32_fp4 v[108:109], v59, 1.0
	v_pk_fma_f32 v[94:95], s[4:5], v[108:109], v[94:95] op_sel_hi:[0,1,1]
	v_cvt_scalef32_pk_f32_fp4 v[108:109], v59, 1.0 op_sel:[1,0,0]
	s_waitcnt vmcnt(9)
	v_dot8c_i32_i4_e32 v12, v64, v0
	v_dot8c_i32_i4_e32 v27, v64, v1
	v_pk_fma_f32 v[96:97], s[4:5], v[108:109], v[96:97] op_sel_hi:[0,1,1]
	v_cvt_scalef32_pk_f32_fp4 v[108:109], v59, 1.0 op_sel:[0,1,0]
	v_cvt_scalef32_pk_f32_fp4 v[58:59], v59, 1.0 op_sel:[1,1,0]
	v_dot8c_i32_i4_e32 v12, v65, v2
	v_dot8c_i32_i4_e32 v27, v65, v3
	v_pk_fma_f32 v[98:99], s[4:5], v[108:109], v[98:99] op_sel_hi:[0,1,1]
	v_pk_fma_f32 v[108:109], s[4:5], v[58:59], v[62:63] op_sel_hi:[0,1,1]
	v_mov_b32_e32 v58, v13
	v_lshl_add_u32 v12, v12, 4, v27
	v_mov_b32_e32 v27, v13
	v_dot8c_i32_i4_e32 v27, v68, v0
	v_dot8c_i32_i4_e32 v58, v68, v1
	v_dot8c_i32_i4_e32 v27, v69, v2
	v_dot8c_i32_i4_e32 v58, v69, v3
	v_mov_b32_e32 v59, v13
	s_waitcnt vmcnt(7)
	v_dot8c_i32_i4_e32 v59, v60, v1
	v_dot8c_i32_i4_e32 v59, v61, v3
	v_lshl_add_u32 v27, v27, 4, v58
	v_mov_b32_e32 v58, v13
	v_dot8c_i32_i4_e32 v58, v60, v0
	v_dot8c_i32_i4_e32 v58, v61, v2
	s_waitcnt vmcnt(4)
	v_lshlrev_b32_e32 v110, 16, v74
	s_nop 0
	v_lshl_add_u32 v58, v58, 4, v59
	v_mov_b32_e32 v59, v13
	v_dot8c_i32_i4_e32 v59, v66, v0
	v_mov_b32_e32 v0, v13
	v_dot8c_i32_i4_e32 v0, v66, v1
	v_dot8c_i32_i4_e32 v59, v67, v2
	v_dot8c_i32_i4_e32 v0, v67, v3
	v_cndmask_b32_e64 v2, v58, v12, s[0:1]
	v_and_b32_e32 v111, 0xffff0000, v74
	v_lshlrev_b32_e32 v74, 16, v75
	v_lshl_add_u32 v0, v59, 4, v0
	v_cndmask_b32_e64 v1, v27, v0, s[0:1]
	v_cndmask_b32_e64 v0, v0, v27, s[0:1]
	v_and_b32_e32 v75, 0xffff0000, v75
	s_waitcnt vmcnt(3)
	v_pk_fma_f32 v[74:75], v[104:105], v[80:81], v[74:75]
	v_add_u32_dpp v0, v0, v1 quad_perm:[1,0,3,2] row_mask:0xf bank_mask:0xf bound_ctrl:1
	v_cndmask_b32_e64 v1, v12, v58, s[0:1]
	v_lshlrev_b32_e32 v104, 16, v76
	v_and_b32_e32 v105, 0xffff0000, v76
	v_add_u32_dpp v1, v2, v1 quad_perm:[1,0,3,2] row_mask:0xf bank_mask:0xf bound_ctrl:1
	v_cndmask_b32_e64 v12, v1, v0, s[2:3]
	v_cndmask_b32_e64 v27, v0, v1, s[2:3]
	global_load_dwordx4 v[0:3], v[24:25], off offset:48
	global_load_dwordx4 v[58:61], v[24:25], off offset:32
	global_load_dwordx4 v[62:65], v[24:25], off offset:16
	global_load_dwordx4 v[66:69], v[24:25], off
	v_pk_fma_f32 v[78:79], v[100:101], v[78:79], v[110:111]
	s_waitcnt vmcnt(5)
	v_pk_fma_f32 v[28:29], v[28:29], v[86:87], v[104:105]
	v_lshlrev_b32_e32 v104, 16, v70
	v_and_b32_e32 v105, 0xffff0000, v70
	v_lshlrev_b32_e32 v70, 16, v71
	v_and_b32_e32 v71, 0xffff0000, v71
	v_pk_mul_f32 v[100:101], v[78:79], v[78:79]
	v_pk_fma_f32 v[70:71], v[96:97], v[84:85], v[70:71]
	v_lshlrev_b32_e32 v96, 16, v72
	v_and_b32_e32 v97, 0xffff0000, v72
	v_pk_mul_f32 v[80:81], v[74:75], v[74:75]
	s_waitcnt vmcnt(4)
	v_pk_fma_f32 v[90:91], v[98:99], v[90:91], v[96:97]
	v_add_f32_e32 v98, v100, v101
	v_add_f32_e32 v80, v80, v98
	v_pk_mul_f32 v[86:87], v[28:29], v[28:29]
	v_lshlrev_b32_e32 v76, 16, v77
	v_and_b32_e32 v77, 0xffff0000, v77
	v_add_f32_e32 v80, v81, v80
	v_pk_fma_f32 v[76:77], v[106:107], v[88:89], v[76:77]
	v_add_f32_e32 v80, v86, v80
	v_pk_mul_f32 v[88:89], v[76:77], v[76:77]
	v_add_f32_e32 v80, v87, v80
	v_pk_fma_f32 v[82:83], v[94:95], v[82:83], v[104:105]
	v_add_f32_e32 v80, v88, v80
	v_pk_mul_f32 v[94:95], v[82:83], v[82:83]
	v_add_f32_e32 v80, v89, v80
	v_add_f32_e32 v80, v94, v80
	v_pk_mul_f32 v[84:85], v[70:71], v[70:71]
	v_add_f32_e32 v80, v95, v80
	v_add_f32_e32 v80, v84, v80
	v_pk_mul_f32 v[96:97], v[90:91], v[90:91]
	v_lshlrev_b32_e32 v72, 16, v73
	v_and_b32_e32 v73, 0xffff0000, v73
	v_add_f32_e32 v80, v85, v80
	v_pk_fma_f32 v[72:73], v[108:109], v[92:93], v[72:73]
	v_add_f32_e32 v80, v96, v80
	v_pk_mul_f32 v[92:93], v[72:73], v[72:73]
	v_add_f32_e32 v80, v97, v80
	v_add_f32_e32 v80, v92, v80
	v_add_f32_e32 v80, v93, v80
	ds_bpermute_b32 v81, v112, v80
	v_add_u32_dpp v12, v27, v12 quad_perm:[2,3,0,1] row_mask:0xf bank_mask:0xf bound_ctrl:1
	s_waitcnt lgkmcnt(0)
	v_add_f32_e32 v80, v80, v81
	ds_bpermute_b32 v81, v113, v80
	v_add_u32_dpp v12, v12, v12 row_ror:4 row_mask:0xf bank_mask:0xf bound_ctrl:1
	s_waitcnt lgkmcnt(0)
	v_add_f32_e32 v80, v80, v81
	v_add_u32_dpp v12, v12, v12 row_ror:8 row_mask:0xf bank_mask:0xf bound_ctrl:1
	v_mov_b32_e32 v27, v12
	ds_bpermute_b32 v81, v114, v80
	s_nop 0
	v_permlane16_swap_b32_e32 v12, v27
	v_add_u32_e32 v12, v12, v27
	v_mov_b32_e32 v27, v12
	s_nop 1
	v_permlane32_swap_b32_e32 v12, v27
	v_add_u32_e32 v12, v27, v12
	s_waitcnt lgkmcnt(0)
	v_add_f32_e32 v27, v80, v81
	ds_bpermute_b32 v80, v115, v27
	v_cvt_f32_i32_e32 v12, v12
	s_waitcnt lgkmcnt(0)
	v_add_f32_e32 v27, v27, v80
	ds_bpermute_b32 v80, v116, v27
	v_mul_f32_e32 v81, v103, v12
	v_fma_f32 v12, |v81|, s39, 1.0
	v_rcp_f32_e32 v12, v12
	s_waitcnt lgkmcnt(0)
	v_add_f32_e32 v27, v27, v80
	ds_bpermute_b32 v80, v117, v27
	v_fmamk_f32 v84, v12, 0x3f07dc22, v129
	v_fmaak_f32 v84, v12, v84, 0x3f35f0e3
	v_fmaak_f32 v84, v12, v84, 0xbe11a98e
	v_fmaak_f32 v84, v12, v84, 0x3e027906
	s_waitcnt lgkmcnt(0)
; __device__ __forceinline__ void p3_axpy(const u32x2 (&vr)[4], float ws, f32x2 (&acc)[8]) {
; #pragma unroll
;     for (int u = 0; u < 4; u++) {
;         const int la = ((u >> 1) & 1) | ((u & 1) << 1);
;         const float wu = __builtin_bit_cast(float, __builtin_amdgcn_readlane(__builtin_bit_cast(int, ws), la));
;         const f32x2 w2 = {wu, wu};
;         const unsigned vw[2] = {vr[u].x, vr[u].y};
; #pragma unroll
;         for (int i = 0; i < 2; i++) {
;             acc[i * 4 + 0] = __builtin_elementwise_fma(w2, __builtin_amdgcn_cvt_scalef32_pk_f32_fp4(vw[i], 1.0f, 0), acc[i * 4 + 0]);
;             acc[i * 4 + 1] = __builtin_elementwise_fma(w2, __builtin_amdgcn_cvt_scalef32_pk_f32_fp4(vw[i], 1.0f, 1), acc[i * 4 + 1]);
;             acc[i * 4 + 2] = __builtin_elementwise_fma(w2, __builtin_amdgcn_cvt_scalef32_pk_f32_fp4(vw[i], 1.0f, 2), acc[i * 4 + 2]);
;             acc[i * 4 + 3] = __builtin_elementwise_fma(w2, __builtin_amdgcn_cvt_scalef32_pk_f32_fp4(vw[i], 1.0f, 3), acc[i * 4 + 3]);
;         }
;     }
; }
; __device__ __forceinline__ void p3_finish(const Params& p, float* dstp, int tok, int lane, const f32x2 (&acc)[8], float* tr) {
;     ...
;     ss = wave_sum(ss);
;     const float rstd = rsqrtf(ss * (1.f / 1024.f) + 1e-6f);
; #pragma unroll
;     for (int i = 0; i < 4; i++) {
;         const int d = d0 + i * 4;
;         const f32x4 fg = *(const f32x4*)(p.final_g + d);
;         f32x4 o;
; #pragma unroll
;         for (int j = 0; j < 4; j++) o[j] = x2[i * 4 + j] * rstd * fg[j];
;         *(f32x4*)(tr + d) = o;
;     }
;     __builtin_amdgcn_fence(__ATOMIC_RELEASE, "wavefront");
;     __builtin_amdgcn_wave_barrier();
;     __builtin_amdgcn_fence(__ATOMIC_ACQUIRE, "wavefront");
; #pragma unroll
;     for (int j = 0; j < 4; j++) {
;         const f32x4 v = *(const f32x4*)(tr + j * 256 + lane * 4);
;         *(f32x4*)(dstp + (size_t)tok * DM + j * 256 + lane * 4) = v;
;     }
;     __builtin_amdgcn_wave_barrier();
	v_add_f32_e32 v27, v27, v80
	v_mul_f32_e32 v12, v12, v84
	v_mul_f32_e32 v84, v81, v81
	v_fmamk_f32 v27, v27, 0x3a800000, v130
	v_mul_f32_e32 v84, 0xbf38aa3b, v84
	v_mul_f32_e32 v80, 0x4b800000, v27
	v_cmp_gt_f32_e32 vcc, s38, v27
	v_exp_f32_e32 v84, v84
	s_nop 0
	v_cndmask_b32_e32 v27, v27, v80, vcc
	v_rsq_f32_e32 v27, v27
	v_mul_f32_e32 v12, v84, v12
	v_mul_f32_e32 v80, v81, v12
	v_fma_f32 v84, -v81, v12, v81
	v_mul_f32_e32 v12, 0x45800000, v27
	v_cndmask_b32_e32 v12, v27, v12, vcc
	v_pk_mul_f32 v[78:79], v[78:79], v[12:13] op_sel_hi:[1,0]
	v_pk_mul_f32 v[74:75], v[74:75], v[12:13] op_sel_hi:[1,0]
	s_waitcnt vmcnt(0)
	v_pk_mul_f32 v[66:67], v[66:67], v[78:79]
	v_pk_mul_f32 v[68:69], v[68:69], v[74:75]
	ds_write_b128 v118, v[66:69]
	v_pk_mul_f32 v[28:29], v[28:29], v[12:13] op_sel_hi:[1,0]
	v_pk_mul_f32 v[66:67], v[76:77], v[12:13] op_sel_hi:[1,0]
	v_pk_mul_f32 v[62:63], v[62:63], v[28:29]
	v_pk_mul_f32 v[64:65], v[64:65], v[66:67]
	ds_write_b128 v118, v[62:65] offset:16
	v_pk_mul_f32 v[28:29], v[82:83], v[12:13] op_sel_hi:[1,0]
	v_pk_mul_f32 v[62:63], v[70:71], v[12:13] op_sel_hi:[1,0]
	v_pk_mul_f32 v[58:59], v[58:59], v[28:29]
	v_pk_mul_f32 v[60:61], v[60:61], v[62:63]
	ds_write_b128 v118, v[58:61] offset:32
	v_pk_mul_f32 v[28:29], v[90:91], v[12:13] op_sel_hi:[1,0]
	v_pk_mul_f32 v[58:59], v[72:73], v[12:13] op_sel_hi:[1,0]
	v_pk_mul_f32 v[0:1], v[0:1], v[28:29]
	v_pk_mul_f32 v[2:3], v[2:3], v[58:59]
	ds_write_b128 v118, v[0:3] offset:48
	ds_read_b128 v[0:3], v128
	ds_read_b128 v[58:61], v128 offset:1024
	ds_read_b128 v[62:65], v128 offset:2048
	ds_read_b128 v[66:69], v128 offset:3072
	v_lshlrev_b64 v[28:29], 12, v[8:9]
	v_lshl_add_u64 v[28:29], v[18:19], 0, v[28:29]
	s_waitcnt lgkmcnt(3)
	global_store_dwordx4 v[28:29], v[0:3], off
	s_waitcnt lgkmcnt(2)
	global_store_dwordx4 v[28:29], v[58:61], off offset:1024
	s_waitcnt lgkmcnt(1)
	global_store_dwordx4 v[28:29], v[62:65], off offset:2048
	s_waitcnt lgkmcnt(0)
	global_store_dwordx4 v[28:29], v[66:69], off offset:3072
	v_lshl_add_u64 v[28:29], v[22:23], 0, v[32:33]
	global_load_dwordx4 v[0:3], v[28:29], off offset:16
	global_load_dwordx4 v[58:61], v[28:29], off
	global_load_dwordx4 v[62:65], v[6:7], off
	v_cmp_gt_f32_e32 vcc, 0, v81
	global_load_dwordx4 v[66:69], v[4:5], off offset:32
	global_load_dwordx4 v[70:73], v[4:5], off offset:16
	v_cndmask_b32_e32 v6, v84, v80, vcc
	v_mul_f32_e32 v9, v102, v6
	v_cvt_scalef32_pk_f32_fp4 v[6:7], v40, 1.0
	v_readlane_b32 s4, v9, 0
	v_add_u32_e32 v8, s36, v8
	s_waitcnt vmcnt(3)
	v_lshlrev_b32_e32 v78, 16, v58
	v_pk_fma_f32 v[28:29], s[4:5], v[6:7], v[52:53] op_sel_hi:[0,1,1]
	v_cvt_scalef32_pk_f32_fp4 v[6:7], v40, 1.0 op_sel:[1,0,0]
	v_pk_fma_f32 v[32:33], s[4:5], v[6:7], v[50:51] op_sel_hi:[0,1,1]
	v_cvt_scalef32_pk_f32_fp4 v[6:7], v40, 1.0 op_sel:[0,1,0]
	v_pk_fma_f32 v[48:49], s[4:5], v[6:7], v[48:49] op_sel_hi:[0,1,1]
	v_cvt_scalef32_pk_f32_fp4 v[6:7], v40, 1.0 op_sel:[1,1,0]
	v_pk_fma_f32 v[46:47], s[4:5], v[6:7], v[46:47] op_sel_hi:[0,1,1]
	v_cvt_scalef32_pk_f32_fp4 v[6:7], v41, 1.0
	v_pk_fma_f32 v[44:45], s[4:5], v[6:7], v[44:45] op_sel_hi:[0,1,1]
	v_cvt_scalef32_pk_f32_fp4 v[6:7], v41, 1.0 op_sel:[1,0,0]
	v_pk_fma_f32 v[42:43], s[4:5], v[6:7], v[42:43] op_sel_hi:[0,1,1]
	v_cvt_scalef32_pk_f32_fp4 v[6:7], v41, 1.0 op_sel:[0,1,0]
	v_pk_fma_f32 v[50:51], s[4:5], v[6:7], v[54:55] op_sel_hi:[0,1,1]
	v_cvt_scalef32_pk_f32_fp4 v[6:7], v41, 1.0 op_sel:[1,1,0]
	v_pk_fma_f32 v[40:41], s[4:5], v[6:7], v[56:57] op_sel_hi:[0,1,1]
	global_load_dwordx4 v[4:7], v[4:5], off offset:48
	v_readlane_b32 s4, v9, 2
	v_cvt_scalef32_pk_f32_fp4 v[52:53], v38, 1.0
	v_and_b32_e32 v79, 0xffff0000, v58
	v_pk_fma_f32 v[28:29], s[4:5], v[52:53], v[28:29] op_sel_hi:[0,1,1]
	v_cvt_scalef32_pk_f32_fp4 v[52:53], v38, 1.0 op_sel:[1,0,0]
	v_pk_fma_f32 v[32:33], s[4:5], v[52:53], v[32:33] op_sel_hi:[0,1,1]
	v_cvt_scalef32_pk_f32_fp4 v[52:53], v38, 1.0 op_sel:[0,1,0]
	v_pk_fma_f32 v[48:49], s[4:5], v[52:53], v[48:49] op_sel_hi:[0,1,1]
	v_cvt_scalef32_pk_f32_fp4 v[52:53], v38, 1.0 op_sel:[1,1,0]
	v_pk_fma_f32 v[46:47], s[4:5], v[52:53], v[46:47] op_sel_hi:[0,1,1]
	v_cvt_scalef32_pk_f32_fp4 v[52:53], v39, 1.0
	v_pk_fma_f32 v[44:45], s[4:5], v[52:53], v[44:45] op_sel_hi:[0,1,1]
	v_cvt_scalef32_pk_f32_fp4 v[52:53], v39, 1.0 op_sel:[1,0,0]
	v_pk_fma_f32 v[42:43], s[4:5], v[52:53], v[42:43] op_sel_hi:[0,1,1]
	v_cvt_scalef32_pk_f32_fp4 v[52:53], v39, 1.0 op_sel:[0,1,0]
	v_cvt_scalef32_pk_f32_fp4 v[38:39], v39, 1.0 op_sel:[1,1,0]
	v_pk_fma_f32 v[50:51], s[4:5], v[52:53], v[50:51] op_sel_hi:[0,1,1]
	v_pk_fma_f32 v[38:39], s[4:5], v[38:39], v[40:41] op_sel_hi:[0,1,1]
	v_readlane_b32 s4, v9, 1
	v_cvt_scalef32_pk_f32_fp4 v[40:41], v36, 1.0
	v_lshlrev_b32_e32 v58, 16, v59
	v_pk_fma_f32 v[28:29], s[4:5], v[40:41], v[28:29] op_sel_hi:[0,1,1]
	v_cvt_scalef32_pk_f32_fp4 v[40:41], v36, 1.0 op_sel:[1,0,0]
	v_pk_fma_f32 v[32:33], s[4:5], v[40:41], v[32:33] op_sel_hi:[0,1,1]
	v_cvt_scalef32_pk_f32_fp4 v[40:41], v36, 1.0 op_sel:[0,1,0]
	v_pk_fma_f32 v[40:41], s[4:5], v[40:41], v[48:49] op_sel_hi:[0,1,1]
	v_cvt_scalef32_pk_f32_fp4 v[48:49], v36, 1.0 op_sel:[1,1,0]
	v_pk_fma_f32 v[46:47], s[4:5], v[48:49], v[46:47] op_sel_hi:[0,1,1]
	v_cvt_scalef32_pk_f32_fp4 v[48:49], v37, 1.0
	v_pk_fma_f32 v[44:45], s[4:5], v[48:49], v[44:45] op_sel_hi:[0,1,1]
	v_cvt_scalef32_pk_f32_fp4 v[48:49], v37, 1.0 op_sel:[1,0,0]
	v_pk_fma_f32 v[42:43], s[4:5], v[48:49], v[42:43] op_sel_hi:[0,1,1]
	v_cvt_scalef32_pk_f32_fp4 v[48:49], v37, 1.0 op_sel:[0,1,0]
	v_cvt_scalef32_pk_f32_fp4 v[36:37], v37, 1.0 op_sel:[1,1,0]
	v_pk_fma_f32 v[48:49], s[4:5], v[48:49], v[50:51] op_sel_hi:[0,1,1]
	v_pk_fma_f32 v[36:37], s[4:5], v[36:37], v[38:39] op_sel_hi:[0,1,1]
	v_readlane_b32 s4, v9, 3
	v_cvt_scalef32_pk_f32_fp4 v[38:39], v34, 1.0
	v_and_b32_e32 v59, 0xffff0000, v59
	v_pk_fma_f32 v[28:29], s[4:5], v[38:39], v[28:29] op_sel_hi:[0,1,1]
	v_cvt_scalef32_pk_f32_fp4 v[38:39], v34, 1.0 op_sel:[1,0,0]
	v_pk_fma_f32 v[50:51], s[4:5], v[38:39], v[32:33] op_sel_hi:[0,1,1]
	v_cvt_scalef32_pk_f32_fp4 v[32:33], v34, 1.0 op_sel:[0,1,0]
	v_pk_fma_f32 v[52:53], s[4:5], v[32:33], v[40:41] op_sel_hi:[0,1,1]
	v_cvt_scalef32_pk_f32_fp4 v[32:33], v34, 1.0 op_sel:[1,1,0]
	v_pk_fma_f32 v[54:55], s[4:5], v[32:33], v[46:47] op_sel_hi:[0,1,1]
	v_cvt_scalef32_pk_f32_fp4 v[32:33], v35, 1.0
	v_pk_fma_f32 v[56:57], s[4:5], v[32:33], v[44:45] op_sel_hi:[0,1,1]
	v_cvt_scalef32_pk_f32_fp4 v[32:33], v35, 1.0 op_sel:[1,0,0]
	v_pk_fma_f32 v[74:75], s[4:5], v[32:33], v[42:43] op_sel_hi:[0,1,1]
	v_cvt_scalef32_pk_f32_fp4 v[32:33], v35, 1.0 op_sel:[0,1,0]
	v_pk_fma_f32 v[48:49], s[4:5], v[32:33], v[48:49] op_sel_hi:[0,1,1]
	v_cvt_scalef32_pk_f32_fp4 v[32:33], v35, 1.0 op_sel:[1,1,0]
	v_pk_fma_f32 v[76:77], s[4:5], v[32:33], v[36:37] op_sel_hi:[0,1,1]
	global_load_dwordx4 v[32:35], v[24:25], off offset:48
	global_load_dwordx4 v[36:39], v[24:25], off offset:32
	global_load_dwordx4 v[40:43], v[24:25], off offset:16
	global_load_dwordx4 v[44:47], v[24:25], off
	s_waitcnt vmcnt(7)
; __device__ __forceinline__ float bf_lo(unsigned u) { return __uint_as_float(u << 16); }
; __device__ __forceinline__ float bf_hi(unsigned u) { return __uint_as_float(u & 0xffff0000u); }
; __device__ __forceinline__ void p3_finish(const Params& p, float* dstp, int tok, int lane, const f32x2 (&acc)[8], float* tr) {
;     ...
;     for (int i = 0; i < 4; i++) {
;         const int d = d0 + i * 4;
;         const f32x4 xv = {bf_lo(xw[2 * i]), bf_hi(xw[2 * i]), bf_lo(xw[2 * i + 1]), bf_hi(xw[2 * i + 1])};
;         const f32x4 gt = *(const f32x4*)(mod + b * 6144 + 5 * 1024 + d);
; #pragma unroll
;         for (int j = 0; j < 4; j++) { const float v = xv[j] + gt[j] * own[i * 4 + j]; x2[i * 4 + j] = v; ss += v * v; }
;     }
;     ss = wave_sum(ss);
;     const float rstd = rsqrtf(ss * (1.f / 1024.f) + 1e-6f);
; #pragma unroll
;     for (int i = 0; i < 4; i++) {
;         const int d = d0 + i * 4;
;         const f32x4 fg = *(const f32x4*)(p.final_g + d);
;         f32x4 o;
; #pragma unroll
;         for (int j = 0; j < 4; j++) o[j] = x2[i * 4 + j] * rstd * fg[j];
;         *(f32x4*)(tr + d) = o;
;     }
;     __builtin_amdgcn_fence(__ATOMIC_RELEASE, "wavefront");
;     __builtin_amdgcn_wave_barrier();
;     __builtin_amdgcn_fence(__ATOMIC_ACQUIRE, "wavefront");
; #pragma unroll
;     for (int j = 0; j < 4; j++) {
;         const f32x4 v = *(const f32x4*)(tr + j * 256 + lane * 4);
;         *(f32x4*)(dstp + (size_t)tok * DM + j * 256 + lane * 4) = v;
;     }
;     __builtin_amdgcn_wave_barrier();
	v_pk_fma_f32 v[28:29], v[28:29], v[62:63], v[78:79]
	v_pk_fma_f32 v[50:51], v[50:51], v[64:65], v[58:59]
	v_pk_mul_f32 v[62:63], v[28:29], v[28:29]
	v_pk_mul_f32 v[58:59], v[50:51], v[50:51]
	v_lshlrev_b32_e32 v64, 16, v60
	v_and_b32_e32 v65, 0xffff0000, v60
	v_add_f32_e32 v9, v62, v63
	s_waitcnt vmcnt(5)
	v_pk_fma_f32 v[52:53], v[52:53], v[70:71], v[64:65]
	v_add_f32_e32 v9, v58, v9
	v_pk_mul_f32 v[64:65], v[52:53], v[52:53]
	v_lshlrev_b32_e32 v60, 16, v61
	v_and_b32_e32 v61, 0xffff0000, v61
	v_add_f32_e32 v9, v59, v9
	v_pk_fma_f32 v[54:55], v[54:55], v[72:73], v[60:61]
	v_add_f32_e32 v9, v64, v9
	v_pk_mul_f32 v[60:61], v[54:55], v[54:55]
	v_lshlrev_b32_e32 v70, 16, v0
	v_and_b32_e32 v71, 0xffff0000, v0
	v_add_f32_e32 v9, v65, v9
	v_pk_fma_f32 v[56:57], v[56:57], v[66:67], v[70:71]
	v_add_f32_e32 v9, v60, v9
	v_pk_mul_f32 v[66:67], v[56:57], v[56:57]
	v_lshlrev_b32_e32 v0, 16, v1
	v_and_b32_e32 v1, 0xffff0000, v1
	v_add_f32_e32 v9, v61, v9
	v_pk_fma_f32 v[68:69], v[74:75], v[68:69], v[0:1]
	v_add_f32_e32 v9, v66, v9
	v_pk_mul_f32 v[0:1], v[68:69], v[68:69]
	v_lshlrev_b32_e32 v70, 16, v2
	v_and_b32_e32 v71, 0xffff0000, v2
	v_add_f32_e32 v9, v67, v9
	s_waitcnt vmcnt(4)
	v_pk_fma_f32 v[4:5], v[48:49], v[4:5], v[70:71]
	v_add_f32_e32 v0, v0, v9
	v_pk_mul_f32 v[48:49], v[4:5], v[4:5]
	v_lshlrev_b32_e32 v2, 16, v3
	v_and_b32_e32 v3, 0xffff0000, v3
	v_add_f32_e32 v0, v1, v0
	v_pk_fma_f32 v[6:7], v[76:77], v[6:7], v[2:3]
	v_add_f32_e32 v0, v48, v0
	v_pk_mul_f32 v[2:3], v[6:7], v[6:7]
	v_add_f32_e32 v0, v49, v0
	v_add_f32_e32 v0, v2, v0
	v_add_f32_e32 v0, v3, v0
	ds_bpermute_b32 v1, v112, v0
	s_waitcnt lgkmcnt(0)
	v_add_f32_e32 v0, v0, v1
	ds_bpermute_b32 v1, v113, v0
	s_waitcnt lgkmcnt(0)
	v_add_f32_e32 v0, v0, v1
	ds_bpermute_b32 v1, v114, v0
	s_waitcnt lgkmcnt(0)
	v_add_f32_e32 v0, v0, v1
	ds_bpermute_b32 v1, v115, v0
	s_waitcnt lgkmcnt(0)
	v_add_f32_e32 v0, v0, v1
	ds_bpermute_b32 v1, v116, v0
	s_waitcnt lgkmcnt(0)
	v_add_f32_e32 v0, v0, v1
	ds_bpermute_b32 v1, v117, v0
	s_waitcnt lgkmcnt(0)
	v_add_f32_e32 v0, v0, v1
	v_fmamk_f32 v0, v0, 0x3a800000, v130
	v_mul_f32_e32 v1, 0x4b800000, v0
	v_cmp_gt_f32_e32 vcc, s38, v0
	s_nop 1
	v_cndmask_b32_e32 v0, v0, v1, vcc
	v_rsq_f32_e32 v0, v0
	s_nop 0
	v_mul_f32_e32 v1, 0x45800000, v0
	v_cndmask_b32_e32 v12, v0, v1, vcc
	v_pk_mul_f32 v[0:1], v[28:29], v[12:13] op_sel_hi:[1,0]
	v_pk_mul_f32 v[2:3], v[50:51], v[12:13] op_sel_hi:[1,0]
	s_waitcnt vmcnt(0)
	v_pk_mul_f32 v[0:1], v[44:45], v[0:1]
	v_pk_mul_f32 v[2:3], v[46:47], v[2:3]
	ds_write_b128 v118, v[0:3]
	v_pk_mul_f32 v[0:1], v[52:53], v[12:13] op_sel_hi:[1,0]
	v_pk_mul_f32 v[2:3], v[54:55], v[12:13] op_sel_hi:[1,0]
	v_pk_mul_f32 v[0:1], v[40:41], v[0:1]
	v_pk_mul_f32 v[2:3], v[42:43], v[2:3]
	ds_write_b128 v118, v[0:3] offset:16
	v_pk_mul_f32 v[0:1], v[56:57], v[12:13] op_sel_hi:[1,0]
	v_pk_mul_f32 v[2:3], v[68:69], v[12:13] op_sel_hi:[1,0]
	v_pk_mul_f32 v[0:1], v[36:37], v[0:1]
	v_pk_mul_f32 v[2:3], v[38:39], v[2:3]
	ds_write_b128 v118, v[0:3] offset:32
	v_pk_mul_f32 v[0:1], v[4:5], v[12:13] op_sel_hi:[1,0]
	v_pk_mul_f32 v[2:3], v[6:7], v[12:13] op_sel_hi:[1,0]
	v_pk_mul_f32 v[0:1], v[32:33], v[0:1]
	v_pk_mul_f32 v[2:3], v[34:35], v[2:3]
	ds_write_b128 v118, v[0:3] offset:48
	ds_read_b128 v[0:3], v128
	ds_read_b128 v[4:7], v128 offset:1024
	v_lshlrev_b64 v[32:33], 12, v[30:31]
	v_lshl_add_u64 v[32:33], v[18:19], 0, v[32:33]
	ds_read_b128 v[28:31], v128 offset:2048
	s_waitcnt lgkmcnt(2)
	global_store_dwordx4 v[32:33], v[0:3], off
	s_waitcnt lgkmcnt(1)
	global_store_dwordx4 v[32:33], v[4:7], off offset:1024
	ds_read_b128 v[0:3], v128 offset:3072
	v_cmp_lt_i32_e32 vcc, s41, v8
	s_or_b64 s[28:29], vcc, s[28:29]
	s_waitcnt lgkmcnt(1)
	global_store_dwordx4 v[32:33], v[28:31], off offset:2048
	s_waitcnt lgkmcnt(0)
	global_store_dwordx4 v[32:33], v[0:3], off offset:3072
	s_andn2_b64 exec, exec, s[28:29]
	s_cbranch_execnz .LBB0_1042
